# v036 + GEMM K-loops: LDS-DMA staging rebalanced 4/4/4/4 (As[b][0] half-tile staged one segment later, retired with vmcnt(4)), dead address setup removed from the critical segments
# baseline (speedup 1.0000x reference)
; #define PG8_STAGE(bufoff, gbase, voff) do { _Pragma("unroll") for (int _i = 0; _i < 2; ++_i) \
;         __builtin_amdgcn_global_load_lds((const unsigned*)((const char*)(gbase) + (voff)[_i]), (PG8_LAS unsigned*)(lds + (bufoff) + ldsw + _i * 8192), 16, 0, 0); } while (0)
; #define PG8_LDA(dst, b, h) do { _Pragma("unroll") for (int m = 0; m < 4; ++m) _Pragma("unroll") for (int k = 0; k < 2; ++k) dst[m][k] = *(const PG8_LAS bf16x8*)(lds + PG8_SA(b, h) + aoff + m * 2048 + k * 1024); } while (0)
; #define PG8_LDB(dst, b, h) do { _Pragma("unroll") for (int n = 0; n < 2; ++n) _Pragma("unroll") for (int k = 0; k < 2; ++k) dst[n][k] = *(const PG8_LAS bf16x8*)(lds + PG8_SB(b, h) + boff + n * 2048 + k * 1024); } while (0)
; #define PG8_MMA(ai, bj, At, Bt) do { __builtin_amdgcn_s_setprio(1); _Pragma("unroll") for (int m = 0; m < 4; ++m) _Pragma("unroll") for (int n = 0; n < 2; ++n) _Pragma("unroll") for (int k = 0; k < 2; ++k) \
;         acc[ai][bj][m][n] = __builtin_amdgcn_mfma_f32_16x16x32_bf16(Bt[n][k], At[m][k], acc[ai][bj][m][n], 0, 0, 0); __builtin_amdgcn_s_setprio(0); } while (0)
; #define PG8_WAIT_V(n) asm volatile("s_waitcnt vmcnt(" #n ")" ::: "memory")
; #define PG8_WAIT_L(n) asm volatile("s_waitcnt lgkmcnt(" #n ")" ::: "memory")
; #define PG8_BAR __builtin_amdgcn_s_barrier()
; #define PG8_SCHED __builtin_amdgcn_sched_barrier(0)
; template <class Epi, class Sched, bool ALIGN_EPI = false, bool SP2 = false>
; __device__ __forceinline__ void gemm_phase(PG8_LAS unsigned char* lds, const Gemm g, const Sched& S, const Epi& E) {
;     ...
;             PG8_LDB(B0, 0, 0); PG8_LDB(B1, 0, 1); PG8_SCHED; PG8_LDA(At, 0, 0); PG8_STAGE(PG8_SA(1, 1), a1 + hstep, voffA);
;             PG8_WAIT_V(8); PG8_WAIT_L(0); PG8_BAR; PG8_MMA(0, 0, At, B0); PG8_MMA(0, 1, At, B1); PG8_BAR; PG8_SCHED;
;             PG8_LDA(At, 0, 1); PG8_STAGE(PG8_SB(0, 0), b2, voffB); PG8_STAGE(PG8_SB(0, 1), b2 + hstep, voffB); PG8_STAGE(PG8_SA(0, 0), a2, voffA);
.LBB0_150:
	ds_read_b128 v[154:157], v150
	ds_read_b128 v[158:161], v150 offset:1024
	ds_read_b128 v[162:165], v150 offset:2048
	ds_read_b128 v[172:175], v150 offset:3072
	ds_read_b128 v[176:179], v151
	ds_read_b128 v[180:183], v151 offset:1024
	ds_read_b128 v[184:187], v151 offset:2048
	ds_read_b128 v[188:191], v151 offset:3072
	s_add_u32 s28, s0, 0xfffc0080
	s_addc_u32 s29, s1, -1
	s_cmp_eq_u32 s51, 12
	s_cselect_b32 s31, s21, s29
	s_cselect_b32 s30, s47, s28
	s_cselect_b32 s29, s19, s50
	s_cselect_b32 s28, s48, s49
	v_lshl_add_u64 v[144:145], s[0:1], 0, v[136:137]
	s_add_i32 m0, s27, 0xc000
	ds_read_b128 v[202:205], v152
	ds_read_b128 v[206:209], v152 offset:1024
	ds_read_b128 v[210:213], v152 offset:2048
	ds_read_b128 v[214:217], v152 offset:3072
	ds_read_b128 v[218:221], v152 offset:4096
	ds_read_b128 v[222:225], v152 offset:5120
	ds_read_b128 v[226:229], v152 offset:6144
	ds_read_b128 v[230:233], v152 offset:7168
	global_load_lds_dwordx4 v[144:145], off
	v_lshl_add_u64 v[144:145], s[0:1], 0, v[138:139]
	s_add_i32 m0, s27, 0xe000
	s_nop 0
	global_load_lds_dwordx4 v[144:145], off
	s_add_u32 s100, s0, 0xfffc0000
	s_addc_u32 s101, s1, -1
	v_lshl_add_u64 v[144:145], s[100:101], 0, v[136:137]
	s_add_i32 m0, s27, 0x8000
	s_nop 0
	global_load_lds_dwordx4 v[144:145], off
	v_lshl_add_u64 v[144:145], s[100:101], 0, v[138:139]
	s_add_i32 m0, s27, 0xa000
	s_nop 0
	global_load_lds_dwordx4 v[144:145], off
	s_waitcnt vmcnt(8)
	s_waitcnt lgkmcnt(0)
	s_barrier
	s_setprio 1
	s_waitcnt lgkmcnt(0)
	v_mfma_f32_16x16x32_bf16 v[124:127], v[154:157], v[202:205], v[124:127]
	v_mfma_f32_16x16x32_bf16 v[120:123], v[162:165], v[202:205], v[120:123]
	v_mfma_f32_16x16x32_bf16 v[108:111], v[154:157], v[210:213], v[108:111]
	v_mfma_f32_16x16x32_bf16 v[104:107], v[162:165], v[210:213], v[104:107]
	v_mfma_f32_16x16x32_bf16 v[92:95], v[154:157], v[218:221], v[92:95]
	v_mfma_f32_16x16x32_bf16 v[88:91], v[162:165], v[218:221], v[88:91]
	v_mfma_f32_16x16x32_bf16 v[76:79], v[154:157], v[226:229], v[76:79]
	v_mfma_f32_16x16x32_bf16 v[72:75], v[162:165], v[226:229], v[72:75]
	v_mfma_f32_16x16x32_bf16 v[124:127], v[158:161], v[206:209], v[124:127]
	v_mfma_f32_16x16x32_bf16 v[120:123], v[172:175], v[206:209], v[120:123]
	v_mfma_f32_16x16x32_bf16 v[108:111], v[158:161], v[214:217], v[108:111]
	v_mfma_f32_16x16x32_bf16 v[104:107], v[172:175], v[214:217], v[104:107]
	v_mfma_f32_16x16x32_bf16 v[92:95], v[158:161], v[222:225], v[92:95]
	v_mfma_f32_16x16x32_bf16 v[88:91], v[172:175], v[222:225], v[88:91]
	v_mfma_f32_16x16x32_bf16 v[76:79], v[158:161], v[230:233], v[76:79]
	v_mfma_f32_16x16x32_bf16 v[72:75], v[172:175], v[230:233], v[72:75]
	s_setprio 0
	s_setprio 1
	v_mfma_f32_16x16x32_bf16 v[116:119], v[176:179], v[202:205], v[116:119]
	v_mfma_f32_16x16x32_bf16 v[112:115], v[184:187], v[202:205], v[112:115]
	v_mfma_f32_16x16x32_bf16 v[100:103], v[176:179], v[210:213], v[100:103]
	v_mfma_f32_16x16x32_bf16 v[96:99], v[184:187], v[210:213], v[96:99]
	v_mfma_f32_16x16x32_bf16 v[84:87], v[176:179], v[218:221], v[84:87]
	v_mfma_f32_16x16x32_bf16 v[80:83], v[184:187], v[218:221], v[80:83]
	v_mfma_f32_16x16x32_bf16 v[68:71], v[176:179], v[226:229], v[68:71]
	v_mfma_f32_16x16x32_bf16 v[64:67], v[184:187], v[226:229], v[64:67]
	v_mfma_f32_16x16x32_bf16 v[116:119], v[180:183], v[206:209], v[116:119]
	v_mfma_f32_16x16x32_bf16 v[112:115], v[188:191], v[206:209], v[112:115]
	v_mfma_f32_16x16x32_bf16 v[100:103], v[180:183], v[214:217], v[100:103]
	v_mfma_f32_16x16x32_bf16 v[96:99], v[188:191], v[214:217], v[96:99]
	v_mfma_f32_16x16x32_bf16 v[84:87], v[180:183], v[222:225], v[84:87]
	v_mfma_f32_16x16x32_bf16 v[80:83], v[188:191], v[222:225], v[80:83]
	v_mfma_f32_16x16x32_bf16 v[68:71], v[180:183], v[230:233], v[68:71]
	v_mfma_f32_16x16x32_bf16 v[64:67], v[188:191], v[230:233], v[64:67]
	s_setprio 0
	s_barrier
	s_add_i32 s52, s44, s34
	v_lshl_add_u64 v[144:145], s[28:29], 0, v[132:133]
	s_mov_b32 m0, s52
	ds_read_b128 v[202:205], v152 offset:16384
	ds_read_b128 v[206:209], v152 offset:17408
	ds_read_b128 v[210:213], v152 offset:18432
	ds_read_b128 v[214:217], v152 offset:19456
	ds_read_b128 v[218:221], v152 offset:20480
	ds_read_b128 v[222:225], v152 offset:21504
	ds_read_b128 v[226:229], v152 offset:22528
	ds_read_b128 v[230:233], v152 offset:23552
	global_load_lds_dwordx4 v[144:145], off
	s_add_i32 m0, s52, 0x2000
	s_add_u32 s52, s28, 0x40000
	v_lshl_add_u64 v[166:167], s[28:29], 0, v[128:129]
	s_addc_u32 s53, s29, 0
	s_add_i32 s54, s45, s34
	global_load_lds_dwordx4 v[166:167], off
	v_lshl_add_u64 v[192:193], s[52:53], 0, v[132:133]
	s_mov_b32 m0, s54
	v_lshl_add_u64 v[196:197], s[30:31], 0, v[130:131]
	global_load_lds_dwordx4 v[192:193], off
	v_lshl_add_u64 v[192:193], s[52:53], 0, v[128:129]
	s_add_i32 m0, s54, 0x2000
	s_nop 0
	global_load_lds_dwordx4 v[192:193], off
	s_waitcnt vmcnt(4)
	s_waitcnt lgkmcnt(0)
	s_barrier
; #define PG8_STAGE(bufoff, gbase, voff) do { _Pragma("unroll") for (int _i = 0; _i < 2; ++_i) \
;         __builtin_amdgcn_global_load_lds((const unsigned*)((const char*)(gbase) + (voff)[_i]), (PG8_LAS unsigned*)(lds + (bufoff) + ldsw + _i * 8192), 16, 0, 0); } while (0)
; #define PG8_LDA(dst, b, h) do { _Pragma("unroll") for (int m = 0; m < 4; ++m) _Pragma("unroll") for (int k = 0; k < 2; ++k) dst[m][k] = *(const PG8_LAS bf16x8*)(lds + PG8_SA(b, h) + aoff + m * 2048 + k * 1024); } while (0)
; #define PG8_LDB(dst, b, h) do { _Pragma("unroll") for (int n = 0; n < 2; ++n) _Pragma("unroll") for (int k = 0; k < 2; ++k) dst[n][k] = *(const PG8_LAS bf16x8*)(lds + PG8_SB(b, h) + boff + n * 2048 + k * 1024); } while (0)
; #define PG8_MMA(ai, bj, At, Bt) do { __builtin_amdgcn_s_setprio(1); _Pragma("unroll") for (int m = 0; m < 4; ++m) _Pragma("unroll") for (int n = 0; n < 2; ++n) _Pragma("unroll") for (int k = 0; k < 2; ++k) \
;         acc[ai][bj][m][n] = __builtin_amdgcn_mfma_f32_16x16x32_bf16(Bt[n][k], At[m][k], acc[ai][bj][m][n], 0, 0, 0); __builtin_amdgcn_s_setprio(0); } while (0)
; #define PG8_WAIT_V(n) asm volatile("s_waitcnt vmcnt(" #n ")" ::: "memory")
; #define PG8_WAIT_L(n) asm volatile("s_waitcnt lgkmcnt(" #n ")" ::: "memory")
; #define PG8_BAR __builtin_amdgcn_s_barrier()
; #define PG8_SCHED __builtin_amdgcn_sched_barrier(0)
; template <class Epi, class Sched, bool ALIGN_EPI = false, bool SP2 = false>
; __device__ __forceinline__ void gemm_phase(PG8_LAS unsigned char* lds, const Gemm g, const Sched& S, const Epi& E) {
;     ...
;             PG8_WAIT_V(8); PG8_WAIT_L(0); PG8_BAR; PG8_MMA(1, 0, At, B0); PG8_MMA(1, 1, At, B1); PG8_BAR; PG8_SCHED;
;             PG8_LDB(B0, 1, 0); PG8_LDB(B1, 1, 1); PG8_SCHED; PG8_LDA(At, 1, 0); PG8_STAGE(PG8_SA(0, 1), a2 + hstep, voffA);
;             PG8_WAIT_V(8); PG8_WAIT_L(0); PG8_BAR; PG8_MMA(0, 0, At, B0); PG8_MMA(0, 1, At, B1); PG8_BAR; PG8_SCHED;
	s_setprio 1
	s_waitcnt lgkmcnt(0)
	v_mfma_f32_16x16x32_bf16 v[60:63], v[154:157], v[202:205], v[60:63]
	v_mfma_f32_16x16x32_bf16 v[56:59], v[162:165], v[202:205], v[56:59]
	v_mfma_f32_16x16x32_bf16 v[44:47], v[154:157], v[210:213], v[44:47]
	v_mfma_f32_16x16x32_bf16 v[40:43], v[162:165], v[210:213], v[40:43]
	v_mfma_f32_16x16x32_bf16 v[28:31], v[154:157], v[218:221], v[28:31]
	v_mfma_f32_16x16x32_bf16 v[24:27], v[162:165], v[218:221], v[24:27]
	v_mfma_f32_16x16x32_bf16 v[12:15], v[154:157], v[226:229], v[12:15]
	v_mfma_f32_16x16x32_bf16 v[8:11], v[162:165], v[226:229], v[8:11]
	v_mfma_f32_16x16x32_bf16 v[60:63], v[158:161], v[206:209], v[60:63]
	v_mfma_f32_16x16x32_bf16 v[56:59], v[172:175], v[206:209], v[56:59]
	v_mfma_f32_16x16x32_bf16 v[44:47], v[158:161], v[214:217], v[44:47]
	v_mfma_f32_16x16x32_bf16 v[40:43], v[172:175], v[214:217], v[40:43]
	v_mfma_f32_16x16x32_bf16 v[28:31], v[158:161], v[222:225], v[28:31]
	v_mfma_f32_16x16x32_bf16 v[24:27], v[172:175], v[222:225], v[24:27]
	v_mfma_f32_16x16x32_bf16 v[12:15], v[158:161], v[230:233], v[12:15]
	v_mfma_f32_16x16x32_bf16 v[8:11], v[172:175], v[230:233], v[8:11]
	s_setprio 0
	s_setprio 1
	v_mfma_f32_16x16x32_bf16 v[52:55], v[176:179], v[202:205], v[52:55]
	v_mfma_f32_16x16x32_bf16 v[48:51], v[184:187], v[202:205], v[48:51]
	v_mfma_f32_16x16x32_bf16 v[36:39], v[176:179], v[210:213], v[36:39]
	v_mfma_f32_16x16x32_bf16 v[32:35], v[184:187], v[210:213], v[32:35]
	v_mfma_f32_16x16x32_bf16 v[20:23], v[176:179], v[218:221], v[20:23]
	v_mfma_f32_16x16x32_bf16 v[16:19], v[184:187], v[218:221], v[16:19]
	v_mfma_f32_16x16x32_bf16 v[4:7], v[176:179], v[226:229], v[4:7]
	v_mfma_f32_16x16x32_bf16 v[0:3], v[184:187], v[226:229], v[0:3]
	v_mfma_f32_16x16x32_bf16 v[52:55], v[180:183], v[206:209], v[52:55]
	v_mfma_f32_16x16x32_bf16 v[48:51], v[188:191], v[206:209], v[48:51]
	v_mfma_f32_16x16x32_bf16 v[36:39], v[180:183], v[214:217], v[36:39]
	v_mfma_f32_16x16x32_bf16 v[32:35], v[188:191], v[214:217], v[32:35]
	v_mfma_f32_16x16x32_bf16 v[20:23], v[180:183], v[222:225], v[20:23]
	v_mfma_f32_16x16x32_bf16 v[16:19], v[188:191], v[222:225], v[16:19]
	v_mfma_f32_16x16x32_bf16 v[4:7], v[180:183], v[230:233], v[4:7]
	v_mfma_f32_16x16x32_bf16 v[0:3], v[188:191], v[230:233], v[0:3]
	s_setprio 0
	s_barrier
	s_add_i32 s52, 0, 0x18000
	v_add_u32_e32 v153, s52, v147
	s_add_i32 s53, 0, 0x1c000
	ds_read_b128 v[154:157], v153
	ds_read_b128 v[158:161], v153 offset:1024
	ds_read_b128 v[162:165], v153 offset:2048
	ds_read_b128 v[172:175], v153 offset:3072
	v_add_u32_e32 v153, s53, v147
	ds_read_b128 v[176:179], v153
	ds_read_b128 v[180:183], v153 offset:1024
	ds_read_b128 v[184:187], v153 offset:2048
	ds_read_b128 v[188:191], v153 offset:3072
	s_add_u32 s30, s30, 0x40000
	s_addc_u32 s31, s31, 0
	s_mov_b32 m0, s38
	v_lshl_add_u64 v[234:235], s[30:31], 0, v[134:135]
	ds_read_b128 v[202:205], v152 offset:32768
	ds_read_b128 v[206:209], v152 offset:33792
	ds_read_b128 v[210:213], v152 offset:34816
	ds_read_b128 v[214:217], v152 offset:35840
	ds_read_b128 v[218:221], v152 offset:36864
	ds_read_b128 v[222:225], v152 offset:37888
	ds_read_b128 v[226:229], v152 offset:38912
	ds_read_b128 v[230:233], v152 offset:39936
	global_load_lds_dwordx4 v[234:235], off
	v_lshl_add_u64 v[234:235], s[30:31], 0, v[130:131]
	s_mov_b32 m0, s39
	s_nop 0
	global_load_lds_dwordx4 v[234:235], off
	s_add_u32 s100, s30, 0xfffc0000
	s_addc_u32 s101, s31, -1
	v_lshl_add_u64 v[234:235], s[100:101], 0, v[134:135]
	s_add_i32 m0, s38, 0xffffc000
	s_nop 0
	global_load_lds_dwordx4 v[234:235], off
	v_lshl_add_u64 v[234:235], s[100:101], 0, v[130:131]
	s_add_i32 m0, s39, 0xffffc000
	s_nop 0
	global_load_lds_dwordx4 v[234:235], off
	s_waitcnt vmcnt(8)
	s_waitcnt lgkmcnt(0)
	s_barrier
; #define PG8_STAGE(bufoff, gbase, voff) do { _Pragma("unroll") for (int _i = 0; _i < 2; ++_i) \
;         __builtin_amdgcn_global_load_lds((const unsigned*)((const char*)(gbase) + (voff)[_i]), (PG8_LAS unsigned*)(lds + (bufoff) + ldsw + _i * 8192), 16, 0, 0); } while (0)
; #define PG8_LDA(dst, b, h) do { _Pragma("unroll") for (int m = 0; m < 4; ++m) _Pragma("unroll") for (int k = 0; k < 2; ++k) dst[m][k] = *(const PG8_LAS bf16x8*)(lds + PG8_SA(b, h) + aoff + m * 2048 + k * 1024); } while (0)
; #define PG8_MMA(ai, bj, At, Bt) do { __builtin_amdgcn_s_setprio(1); _Pragma("unroll") for (int m = 0; m < 4; ++m) _Pragma("unroll") for (int n = 0; n < 2; ++n) _Pragma("unroll") for (int k = 0; k < 2; ++k) \
;         acc[ai][bj][m][n] = __builtin_amdgcn_mfma_f32_16x16x32_bf16(Bt[n][k], At[m][k], acc[ai][bj][m][n], 0, 0, 0); __builtin_amdgcn_s_setprio(0); } while (0)
; #define PG8_WAIT_V(n) asm volatile("s_waitcnt vmcnt(" #n ")" ::: "memory")
; #define PG8_WAIT_L(n) asm volatile("s_waitcnt lgkmcnt(" #n ")" ::: "memory")
; #define PG8_BAR __builtin_amdgcn_s_barrier()
; #define PG8_SCHED __builtin_amdgcn_sched_barrier(0)
; template <class Epi, class Sched, bool ALIGN_EPI = false, bool SP2 = false>
; __device__ __forceinline__ void gemm_phase(PG8_LAS unsigned char* lds, const Gemm g, const Sched& S, const Epi& E) {
;     ...
;             PG8_WAIT_V(8); PG8_WAIT_L(0); PG8_BAR; PG8_MMA(0, 0, At, B0); PG8_MMA(0, 1, At, B1); PG8_BAR; PG8_SCHED;
;             PG8_LDA(At, 1, 1); PG8_STAGE(PG8_SB(1, 0), b3, voffB); PG8_STAGE(PG8_SB(1, 1), b3 + hstep, voffB); PG8_STAGE(PG8_SA(1, 0), a3, voffA);
;             PG8_WAIT_V(8); PG8_WAIT_L(0); PG8_BAR; PG8_MMA(1, 0, At, B0); PG8_MMA(1, 1, At, B1); PG8_BAR; PG8_SCHED;
	s_setprio 1
	s_waitcnt lgkmcnt(0)
	v_mfma_f32_16x16x32_bf16 v[124:127], v[154:157], v[202:205], v[124:127]
	v_mfma_f32_16x16x32_bf16 v[120:123], v[162:165], v[202:205], v[120:123]
	v_mfma_f32_16x16x32_bf16 v[108:111], v[154:157], v[210:213], v[108:111]
	v_mfma_f32_16x16x32_bf16 v[104:107], v[162:165], v[210:213], v[104:107]
	v_mfma_f32_16x16x32_bf16 v[92:95], v[154:157], v[218:221], v[92:95]
	v_mfma_f32_16x16x32_bf16 v[88:91], v[162:165], v[218:221], v[88:91]
	v_mfma_f32_16x16x32_bf16 v[76:79], v[154:157], v[226:229], v[76:79]
	v_mfma_f32_16x16x32_bf16 v[72:75], v[162:165], v[226:229], v[72:75]
	v_mfma_f32_16x16x32_bf16 v[124:127], v[158:161], v[206:209], v[124:127]
	v_mfma_f32_16x16x32_bf16 v[120:123], v[172:175], v[206:209], v[120:123]
	v_mfma_f32_16x16x32_bf16 v[108:111], v[158:161], v[214:217], v[108:111]
	v_mfma_f32_16x16x32_bf16 v[104:107], v[172:175], v[214:217], v[104:107]
	v_mfma_f32_16x16x32_bf16 v[92:95], v[158:161], v[222:225], v[92:95]
	v_mfma_f32_16x16x32_bf16 v[88:91], v[172:175], v[222:225], v[88:91]
	v_mfma_f32_16x16x32_bf16 v[76:79], v[158:161], v[230:233], v[76:79]
	v_mfma_f32_16x16x32_bf16 v[72:75], v[172:175], v[230:233], v[72:75]
	s_setprio 0
	s_setprio 1
	v_mfma_f32_16x16x32_bf16 v[116:119], v[176:179], v[202:205], v[116:119]
	v_mfma_f32_16x16x32_bf16 v[112:115], v[184:187], v[202:205], v[112:115]
	v_mfma_f32_16x16x32_bf16 v[100:103], v[176:179], v[210:213], v[100:103]
	v_mfma_f32_16x16x32_bf16 v[96:99], v[184:187], v[210:213], v[96:99]
	v_mfma_f32_16x16x32_bf16 v[84:87], v[176:179], v[218:221], v[84:87]
	v_mfma_f32_16x16x32_bf16 v[80:83], v[184:187], v[218:221], v[80:83]
	v_mfma_f32_16x16x32_bf16 v[68:71], v[176:179], v[226:229], v[68:71]
	v_mfma_f32_16x16x32_bf16 v[64:67], v[184:187], v[226:229], v[64:67]
	v_mfma_f32_16x16x32_bf16 v[116:119], v[180:183], v[206:209], v[116:119]
	v_mfma_f32_16x16x32_bf16 v[112:115], v[188:191], v[206:209], v[112:115]
	v_mfma_f32_16x16x32_bf16 v[100:103], v[180:183], v[214:217], v[100:103]
	v_mfma_f32_16x16x32_bf16 v[96:99], v[188:191], v[214:217], v[96:99]
	v_mfma_f32_16x16x32_bf16 v[84:87], v[180:183], v[222:225], v[84:87]
	v_mfma_f32_16x16x32_bf16 v[80:83], v[188:191], v[222:225], v[80:83]
	v_mfma_f32_16x16x32_bf16 v[68:71], v[180:183], v[230:233], v[68:71]
	v_mfma_f32_16x16x32_bf16 v[64:67], v[188:191], v[230:233], v[64:67]
	s_setprio 0
	s_barrier
	s_add_i32 s30, s52, s34
	v_lshl_add_u64 v[144:145], v[144:145], 0, s[10:11]
	s_mov_b32 m0, s30
	ds_read_b128 v[202:205], v152 offset:49152
	ds_read_b128 v[206:209], v152 offset:50176
	ds_read_b128 v[210:213], v152 offset:51200
	ds_read_b128 v[214:217], v152 offset:52224
	ds_read_b128 v[218:221], v152 offset:53248
	ds_read_b128 v[222:225], v152 offset:54272
	ds_read_b128 v[226:229], v152 offset:55296
	ds_read_b128 v[230:233], v152 offset:56320
	global_load_lds_dwordx4 v[144:145], off
	s_add_i32 m0, s30, 0x2000
	s_add_u32 s28, s28, 0x40080
	v_lshl_add_u64 v[144:145], v[166:167], 0, s[10:11]
	s_addc_u32 s29, s29, 0
	s_add_i32 s30, s53, s34
	global_load_lds_dwordx4 v[144:145], off
	v_lshl_add_u64 v[144:145], s[28:29], 0, v[132:133]
	s_mov_b32 m0, s30
	s_nop 0
	global_load_lds_dwordx4 v[144:145], off
	v_lshl_add_u64 v[144:145], s[28:29], 0, v[128:129]
	s_add_i32 m0, s30, 0x2000
	s_nop 0
	global_load_lds_dwordx4 v[144:145], off
	s_waitcnt vmcnt(4)
	s_waitcnt lgkmcnt(0)
	s_barrier
	s_setprio 1
	s_waitcnt lgkmcnt(0)
	v_mfma_f32_16x16x32_bf16 v[60:63], v[154:157], v[202:205], v[60:63]
	v_mfma_f32_16x16x32_bf16 v[56:59], v[162:165], v[202:205], v[56:59]
	v_mfma_f32_16x16x32_bf16 v[44:47], v[154:157], v[210:213], v[44:47]
	v_mfma_f32_16x16x32_bf16 v[40:43], v[162:165], v[210:213], v[40:43]
	v_mfma_f32_16x16x32_bf16 v[28:31], v[154:157], v[218:221], v[28:31]
	v_mfma_f32_16x16x32_bf16 v[24:27], v[162:165], v[218:221], v[24:27]
	v_mfma_f32_16x16x32_bf16 v[12:15], v[154:157], v[226:229], v[12:15]
	v_mfma_f32_16x16x32_bf16 v[8:11], v[162:165], v[226:229], v[8:11]
	v_mfma_f32_16x16x32_bf16 v[60:63], v[158:161], v[206:209], v[60:63]
	v_mfma_f32_16x16x32_bf16 v[56:59], v[172:175], v[206:209], v[56:59]
	v_mfma_f32_16x16x32_bf16 v[44:47], v[158:161], v[214:217], v[44:47]
	v_mfma_f32_16x16x32_bf16 v[40:43], v[172:175], v[214:217], v[40:43]
	v_mfma_f32_16x16x32_bf16 v[28:31], v[158:161], v[222:225], v[28:31]
	v_mfma_f32_16x16x32_bf16 v[24:27], v[172:175], v[222:225], v[24:27]
	v_mfma_f32_16x16x32_bf16 v[12:15], v[158:161], v[230:233], v[12:15]
	v_mfma_f32_16x16x32_bf16 v[8:11], v[172:175], v[230:233], v[8:11]
	s_setprio 0
	s_setprio 1
	v_mfma_f32_16x16x32_bf16 v[52:55], v[176:179], v[202:205], v[52:55]
	v_mfma_f32_16x16x32_bf16 v[48:51], v[184:187], v[202:205], v[48:51]
	v_mfma_f32_16x16x32_bf16 v[36:39], v[176:179], v[210:213], v[36:39]
	v_mfma_f32_16x16x32_bf16 v[32:35], v[184:187], v[210:213], v[32:35]
	v_mfma_f32_16x16x32_bf16 v[20:23], v[176:179], v[218:221], v[20:23]
	v_mfma_f32_16x16x32_bf16 v[16:19], v[184:187], v[218:221], v[16:19]
	v_mfma_f32_16x16x32_bf16 v[4:7], v[176:179], v[226:229], v[4:7]
	v_mfma_f32_16x16x32_bf16 v[0:3], v[184:187], v[226:229], v[0:3]
	v_mfma_f32_16x16x32_bf16 v[52:55], v[180:183], v[206:209], v[52:55]
	v_mfma_f32_16x16x32_bf16 v[48:51], v[188:191], v[206:209], v[48:51]
	v_mfma_f32_16x16x32_bf16 v[36:39], v[180:183], v[214:217], v[36:39]
	v_mfma_f32_16x16x32_bf16 v[32:35], v[188:191], v[214:217], v[32:35]
	v_mfma_f32_16x16x32_bf16 v[20:23], v[180:183], v[222:225], v[20:23]
	v_mfma_f32_16x16x32_bf16 v[16:19], v[188:191], v[222:225], v[16:19]
	v_mfma_f32_16x16x32_bf16 v[4:7], v[180:183], v[230:233], v[4:7]
	v_mfma_f32_16x16x32_bf16 v[0:3], v[188:191], v[230:233], v[0:3]
	s_setprio 0
	s_barrier
	s_add_i32 s51, s51, 2
	s_add_u32 s0, s0, 0x100
	s_addc_u32 s1, s1, 0
	s_add_u32 s49, s49, 0x100
	s_addc_u32 s50, s50, 0
	s_cmp_gt_u32 s51, 13
	s_cbranch_scc0 .LBB0_150
	s_and_b64 vcc, exec, s[12:13]
	s_cbranch_vccz .LBB0_153
	s_barrier

; #define PG8_STAGE(bufoff, gbase, voff) do { _Pragma("unroll") for (int _i = 0; _i < 2; ++_i) \
;         __builtin_amdgcn_global_load_lds((const unsigned*)((const char*)(gbase) + (voff)[_i]), (PG8_LAS unsigned*)(lds + (bufoff) + ldsw + _i * 8192), 16, 0, 0); } while (0)
; #define PG8_LDA(dst, b, h) do { _Pragma("unroll") for (int m = 0; m < 4; ++m) _Pragma("unroll") for (int k = 0; k < 2; ++k) dst[m][k] = *(const PG8_LAS bf16x8*)(lds + PG8_SA(b, h) + aoff + m * 2048 + k * 1024); } while (0)
; #define PG8_LDB(dst, b, h) do { _Pragma("unroll") for (int n = 0; n < 2; ++n) _Pragma("unroll") for (int k = 0; k < 2; ++k) dst[n][k] = *(const PG8_LAS bf16x8*)(lds + PG8_SB(b, h) + boff + n * 2048 + k * 1024); } while (0)
; #define PG8_MMA(ai, bj, At, Bt) do { __builtin_amdgcn_s_setprio(1); _Pragma("unroll") for (int m = 0; m < 4; ++m) _Pragma("unroll") for (int n = 0; n < 2; ++n) _Pragma("unroll") for (int k = 0; k < 2; ++k) \
;         acc[ai][bj][m][n] = __builtin_amdgcn_mfma_f32_16x16x32_bf16(Bt[n][k], At[m][k], acc[ai][bj][m][n], 0, 0, 0); __builtin_amdgcn_s_setprio(0); } while (0)
; #define PG8_WAIT_V(n) asm volatile("s_waitcnt vmcnt(" #n ")" ::: "memory")
; #define PG8_WAIT_L(n) asm volatile("s_waitcnt lgkmcnt(" #n ")" ::: "memory")
; #define PG8_BAR __builtin_amdgcn_s_barrier()
; #define PG8_SCHED __builtin_amdgcn_sched_barrier(0)
; template <class Epi, class Sched, bool ALIGN_EPI = false, bool SP2 = false>
; __device__ __forceinline__ void gemm_phase(PG8_LAS unsigned char* lds, const Gemm g, const Sched& S, const Epi& E) {
;     ...
;             PG8_LDB(B0, 0, 0); PG8_LDB(B1, 0, 1); PG8_SCHED; PG8_LDA(At, 0, 0); PG8_STAGE(PG8_SA(1, 1), a1 + hstep, voffA);
;             PG8_WAIT_V(8); PG8_WAIT_L(0); PG8_BAR; PG8_MMA(0, 0, At, B0); PG8_MMA(0, 1, At, B1); PG8_BAR; PG8_SCHED;
;             PG8_LDA(At, 0, 1); PG8_STAGE(PG8_SB(0, 0), b2, voffB); PG8_STAGE(PG8_SB(0, 1), b2 + hstep, voffB); PG8_STAGE(PG8_SA(0, 0), a2, voffA);
.LBB0_232:
	ds_read_b128 v[128:131], v218
	ds_read_b128 v[132:135], v218 offset:1024
	ds_read_b128 v[136:139], v218 offset:2048
	ds_read_b128 v[140:143], v218 offset:3072
	ds_read_b128 v[144:147], v219
	ds_read_b128 v[148:151], v219 offset:1024
	ds_read_b128 v[152:155], v219 offset:2048
	ds_read_b128 v[156:159], v219 offset:3072
	s_add_u32 s30, s0, 0x100
	s_addc_u32 s31, s1, 0
	s_cmp_eq_u32 s55, 40
	s_cselect_b32 s37, s13, s31
	s_cselect_b32 s36, s12, s30
	s_cselect_b32 s35, s29, s54
	s_cselect_b32 s34, s28, s33
	v_lshl_add_u64 v[192:193], s[0:1], 0, v[182:183]
	s_add_i32 m0, s39, 0xc000
	ds_read_b128 v[160:163], v220
	ds_read_b128 v[164:167], v220 offset:1024
	ds_read_b128 v[188:191], v220 offset:2048
	ds_read_b128 v[226:229], v220 offset:3072
	ds_read_b128 v[230:233], v220 offset:4096
	ds_read_b128 v[234:237], v220 offset:5120
	ds_read_b128 v[238:241], v220 offset:6144
	ds_read_b128 v[242:245], v220 offset:7168
	global_load_lds_dwordx4 v[192:193], off
	v_lshl_add_u64 v[192:193], s[0:1], 0, v[184:185]
	s_add_i32 m0, s39, 0xe000
	s_nop 0
	global_load_lds_dwordx4 v[192:193], off
	s_add_u32 s100, s0, 0xfff50000
	s_addc_u32 s101, s1, -1
	v_lshl_add_u64 v[192:193], s[100:101], 0, v[182:183]
	s_add_i32 m0, s39, 0x8000
	s_nop 0
	global_load_lds_dwordx4 v[192:193], off
	v_lshl_add_u64 v[192:193], s[100:101], 0, v[184:185]
	s_add_i32 m0, s39, 0xa000
	s_nop 0
	global_load_lds_dwordx4 v[192:193], off
	s_waitcnt vmcnt(8)
	s_waitcnt lgkmcnt(0)
	s_barrier
	s_setprio 1
	s_waitcnt lgkmcnt(0)
	v_mfma_f32_16x16x32_bf16 v[124:127], v[128:131], v[160:163], v[124:127]
	v_mfma_f32_16x16x32_bf16 v[120:123], v[136:139], v[160:163], v[120:123]
	v_mfma_f32_16x16x32_bf16 v[108:111], v[128:131], v[188:191], v[108:111]
	v_mfma_f32_16x16x32_bf16 v[104:107], v[136:139], v[188:191], v[104:107]
	v_mfma_f32_16x16x32_bf16 v[92:95], v[128:131], v[230:233], v[92:95]
	v_mfma_f32_16x16x32_bf16 v[88:91], v[136:139], v[230:233], v[88:91]
	v_mfma_f32_16x16x32_bf16 v[76:79], v[128:131], v[238:241], v[76:79]
	v_mfma_f32_16x16x32_bf16 v[72:75], v[136:139], v[238:241], v[72:75]
	v_mfma_f32_16x16x32_bf16 v[124:127], v[132:135], v[164:167], v[124:127]
	v_mfma_f32_16x16x32_bf16 v[120:123], v[140:143], v[164:167], v[120:123]
	v_mfma_f32_16x16x32_bf16 v[108:111], v[132:135], v[226:229], v[108:111]
	v_mfma_f32_16x16x32_bf16 v[104:107], v[140:143], v[226:229], v[104:107]
	v_mfma_f32_16x16x32_bf16 v[92:95], v[132:135], v[234:237], v[92:95]
	v_mfma_f32_16x16x32_bf16 v[88:91], v[140:143], v[234:237], v[88:91]
	v_mfma_f32_16x16x32_bf16 v[76:79], v[132:135], v[242:245], v[76:79]
	v_mfma_f32_16x16x32_bf16 v[72:75], v[140:143], v[242:245], v[72:75]
	s_setprio 0
	s_setprio 1
	v_mfma_f32_16x16x32_bf16 v[116:119], v[144:147], v[160:163], v[116:119]
	v_mfma_f32_16x16x32_bf16 v[112:115], v[152:155], v[160:163], v[112:115]
	v_mfma_f32_16x16x32_bf16 v[100:103], v[144:147], v[188:191], v[100:103]
	v_mfma_f32_16x16x32_bf16 v[96:99], v[152:155], v[188:191], v[96:99]
	v_mfma_f32_16x16x32_bf16 v[84:87], v[144:147], v[230:233], v[84:87]
	v_mfma_f32_16x16x32_bf16 v[80:83], v[152:155], v[230:233], v[80:83]
	v_mfma_f32_16x16x32_bf16 v[68:71], v[144:147], v[238:241], v[68:71]
	v_mfma_f32_16x16x32_bf16 v[64:67], v[152:155], v[238:241], v[64:67]
	v_mfma_f32_16x16x32_bf16 v[116:119], v[148:151], v[164:167], v[116:119]
	v_mfma_f32_16x16x32_bf16 v[112:115], v[156:159], v[164:167], v[112:115]
	v_mfma_f32_16x16x32_bf16 v[100:103], v[148:151], v[226:229], v[100:103]
	v_mfma_f32_16x16x32_bf16 v[96:99], v[156:159], v[226:229], v[96:99]
	v_mfma_f32_16x16x32_bf16 v[84:87], v[148:151], v[234:237], v[84:87]
	v_mfma_f32_16x16x32_bf16 v[80:83], v[156:159], v[234:237], v[80:83]
	v_mfma_f32_16x16x32_bf16 v[68:71], v[148:151], v[242:245], v[68:71]
	v_mfma_f32_16x16x32_bf16 v[64:67], v[156:159], v[242:245], v[64:67]
	s_setprio 0
	s_barrier
	s_add_i32 s0, s48, s38
	v_lshl_add_u64 v[192:193], s[34:35], 0, v[174:175]
	s_mov_b32 m0, s0
	ds_read_b128 v[160:163], v220 offset:16384
	ds_read_b128 v[164:167], v220 offset:17408
	ds_read_b128 v[188:191], v220 offset:18432
	ds_read_b128 v[226:229], v220 offset:19456
	ds_read_b128 v[230:233], v220 offset:20480
	ds_read_b128 v[234:237], v220 offset:21504
	ds_read_b128 v[238:241], v220 offset:22528
	ds_read_b128 v[242:245], v220 offset:23552
	global_load_lds_dwordx4 v[192:193], off
	s_add_i32 m0, s0, 0x2000
	s_add_u32 s0, s34, 0xb0000
	v_lshl_add_u64 v[246:247], s[34:35], 0, v[178:179]
	s_addc_u32 s1, s35, 0
	s_add_i32 s56, s49, s38
	global_load_lds_dwordx4 v[246:247], off
	v_lshl_add_u64 v[248:249], s[0:1], 0, v[174:175]
	s_mov_b32 m0, s56
	v_lshl_add_u64 v[250:251], s[36:37], 0, v[176:177]
	global_load_lds_dwordx4 v[248:249], off
	v_lshl_add_u64 v[248:249], s[0:1], 0, v[178:179]
	s_add_i32 m0, s56, 0x2000
	s_nop 0
	global_load_lds_dwordx4 v[248:249], off
	s_waitcnt vmcnt(4)
	s_waitcnt lgkmcnt(0)
	s_barrier
; #define PG8_STAGE(bufoff, gbase, voff) do { _Pragma("unroll") for (int _i = 0; _i < 2; ++_i) \
;         __builtin_amdgcn_global_load_lds((const unsigned*)((const char*)(gbase) + (voff)[_i]), (PG8_LAS unsigned*)(lds + (bufoff) + ldsw + _i * 8192), 16, 0, 0); } while (0)
; #define PG8_LDA(dst, b, h) do { _Pragma("unroll") for (int m = 0; m < 4; ++m) _Pragma("unroll") for (int k = 0; k < 2; ++k) dst[m][k] = *(const PG8_LAS bf16x8*)(lds + PG8_SA(b, h) + aoff + m * 2048 + k * 1024); } while (0)
; #define PG8_LDB(dst, b, h) do { _Pragma("unroll") for (int n = 0; n < 2; ++n) _Pragma("unroll") for (int k = 0; k < 2; ++k) dst[n][k] = *(const PG8_LAS bf16x8*)(lds + PG8_SB(b, h) + boff + n * 2048 + k * 1024); } while (0)
; #define PG8_MMA(ai, bj, At, Bt) do { __builtin_amdgcn_s_setprio(1); _Pragma("unroll") for (int m = 0; m < 4; ++m) _Pragma("unroll") for (int n = 0; n < 2; ++n) _Pragma("unroll") for (int k = 0; k < 2; ++k) \
;         acc[ai][bj][m][n] = __builtin_amdgcn_mfma_f32_16x16x32_bf16(Bt[n][k], At[m][k], acc[ai][bj][m][n], 0, 0, 0); __builtin_amdgcn_s_setprio(0); } while (0)
; #define PG8_WAIT_V(n) asm volatile("s_waitcnt vmcnt(" #n ")" ::: "memory")
; #define PG8_WAIT_L(n) asm volatile("s_waitcnt lgkmcnt(" #n ")" ::: "memory")
; #define PG8_BAR __builtin_amdgcn_s_barrier()
; #define PG8_SCHED __builtin_amdgcn_sched_barrier(0)
; template <class Epi, class Sched, bool ALIGN_EPI = false, bool SP2 = false>
; __device__ __forceinline__ void gemm_phase(PG8_LAS unsigned char* lds, const Gemm g, const Sched& S, const Epi& E) {
;     ...
;             PG8_WAIT_V(8); PG8_WAIT_L(0); PG8_BAR; PG8_MMA(1, 0, At, B0); PG8_MMA(1, 1, At, B1); PG8_BAR; PG8_SCHED;
;             PG8_LDB(B0, 1, 0); PG8_LDB(B1, 1, 1); PG8_SCHED; PG8_LDA(At, 1, 0); PG8_STAGE(PG8_SA(0, 1), a2 + hstep, voffA);
;             PG8_WAIT_V(8); PG8_WAIT_L(0); PG8_BAR; PG8_MMA(0, 0, At, B0); PG8_MMA(0, 1, At, B1); PG8_BAR; PG8_SCHED;
	s_setprio 1
	s_waitcnt lgkmcnt(0)
	v_mfma_f32_16x16x32_bf16 v[60:63], v[128:131], v[160:163], v[60:63]
	v_mfma_f32_16x16x32_bf16 v[56:59], v[136:139], v[160:163], v[56:59]
	v_mfma_f32_16x16x32_bf16 v[44:47], v[128:131], v[188:191], v[44:47]
	v_mfma_f32_16x16x32_bf16 v[40:43], v[136:139], v[188:191], v[40:43]
	v_mfma_f32_16x16x32_bf16 v[28:31], v[128:131], v[230:233], v[28:31]
	v_mfma_f32_16x16x32_bf16 v[24:27], v[136:139], v[230:233], v[24:27]
	v_mfma_f32_16x16x32_bf16 v[12:15], v[128:131], v[238:241], v[12:15]
	v_mfma_f32_16x16x32_bf16 v[8:11], v[136:139], v[238:241], v[8:11]
	v_mfma_f32_16x16x32_bf16 v[60:63], v[132:135], v[164:167], v[60:63]
	v_mfma_f32_16x16x32_bf16 v[56:59], v[140:143], v[164:167], v[56:59]
	v_mfma_f32_16x16x32_bf16 v[44:47], v[132:135], v[226:229], v[44:47]
	v_mfma_f32_16x16x32_bf16 v[40:43], v[140:143], v[226:229], v[40:43]
	v_mfma_f32_16x16x32_bf16 v[28:31], v[132:135], v[234:237], v[28:31]
	v_mfma_f32_16x16x32_bf16 v[24:27], v[140:143], v[234:237], v[24:27]
	v_mfma_f32_16x16x32_bf16 v[12:15], v[132:135], v[242:245], v[12:15]
	v_mfma_f32_16x16x32_bf16 v[8:11], v[140:143], v[242:245], v[8:11]
	s_setprio 0
	s_setprio 1
	v_mfma_f32_16x16x32_bf16 v[52:55], v[144:147], v[160:163], v[52:55]
	v_mfma_f32_16x16x32_bf16 v[48:51], v[152:155], v[160:163], v[48:51]
	v_mfma_f32_16x16x32_bf16 v[36:39], v[144:147], v[188:191], v[36:39]
	v_mfma_f32_16x16x32_bf16 v[32:35], v[152:155], v[188:191], v[32:35]
	v_mfma_f32_16x16x32_bf16 v[20:23], v[144:147], v[230:233], v[20:23]
	v_mfma_f32_16x16x32_bf16 v[16:19], v[152:155], v[230:233], v[16:19]
	v_mfma_f32_16x16x32_bf16 v[4:7], v[144:147], v[238:241], v[4:7]
	v_mfma_f32_16x16x32_bf16 v[0:3], v[152:155], v[238:241], v[0:3]
	v_mfma_f32_16x16x32_bf16 v[52:55], v[148:151], v[164:167], v[52:55]
	v_mfma_f32_16x16x32_bf16 v[48:51], v[156:159], v[164:167], v[48:51]
	v_mfma_f32_16x16x32_bf16 v[36:39], v[148:151], v[226:229], v[36:39]
	v_mfma_f32_16x16x32_bf16 v[32:35], v[156:159], v[226:229], v[32:35]
	v_mfma_f32_16x16x32_bf16 v[20:23], v[148:151], v[234:237], v[20:23]
	v_mfma_f32_16x16x32_bf16 v[16:19], v[156:159], v[234:237], v[16:19]
	v_mfma_f32_16x16x32_bf16 v[4:7], v[148:151], v[242:245], v[4:7]
	v_mfma_f32_16x16x32_bf16 v[0:3], v[156:159], v[242:245], v[0:3]
	s_setprio 0
	s_barrier
	s_add_i32 s56, 0, 0x18000
	s_add_i32 s57, 0, 0x1c000
	v_add_u32_e32 v140, s56, v196
	v_add_u32_e32 v156, s57, v196
	ds_read_b128 v[128:131], v140
	ds_read_b128 v[132:135], v140 offset:1024
	ds_read_b128 v[136:139], v140 offset:2048
	ds_read_b128 v[140:143], v140 offset:3072
	ds_read_b128 v[144:147], v156
	ds_read_b128 v[148:151], v156 offset:1024
	ds_read_b128 v[152:155], v156 offset:2048
	ds_read_b128 v[156:159], v156 offset:3072
	s_add_u32 s0, s36, 0xb0000
	s_addc_u32 s1, s37, 0
	s_mov_b32 m0, s41
	v_lshl_add_u64 v[252:253], s[0:1], 0, v[172:173]
	ds_read_b128 v[160:163], v220 offset:32768
	ds_read_b128 v[164:167], v220 offset:33792
	ds_read_b128 v[188:191], v220 offset:34816
	ds_read_b128 v[226:229], v220 offset:35840
	ds_read_b128 v[230:233], v220 offset:36864
	ds_read_b128 v[234:237], v220 offset:37888
	ds_read_b128 v[238:241], v220 offset:38912
	ds_read_b128 v[242:245], v220 offset:39936
	global_load_lds_dwordx4 v[252:253], off
	v_lshl_add_u64 v[252:253], s[0:1], 0, v[176:177]
	s_mov_b32 m0, s42
	s_nop 0
	global_load_lds_dwordx4 v[252:253], off
	s_add_u32 s100, s0, 0xfff50000
	s_addc_u32 s101, s1, -1
	v_lshl_add_u64 v[252:253], s[100:101], 0, v[172:173]
	s_add_i32 m0, s41, 0xffffc000
	s_nop 0
	global_load_lds_dwordx4 v[252:253], off
	v_lshl_add_u64 v[252:253], s[100:101], 0, v[176:177]
	s_add_i32 m0, s42, 0xffffc000
	s_nop 0
	global_load_lds_dwordx4 v[252:253], off
	s_waitcnt vmcnt(8)
	s_waitcnt lgkmcnt(0)
	s_barrier
; #define PG8_STAGE(bufoff, gbase, voff) do { _Pragma("unroll") for (int _i = 0; _i < 2; ++_i) \
;         __builtin_amdgcn_global_load_lds((const unsigned*)((const char*)(gbase) + (voff)[_i]), (PG8_LAS unsigned*)(lds + (bufoff) + ldsw + _i * 8192), 16, 0, 0); } while (0)
; #define PG8_LDA(dst, b, h) do { _Pragma("unroll") for (int m = 0; m < 4; ++m) _Pragma("unroll") for (int k = 0; k < 2; ++k) dst[m][k] = *(const PG8_LAS bf16x8*)(lds + PG8_SA(b, h) + aoff + m * 2048 + k * 1024); } while (0)
; #define PG8_MMA(ai, bj, At, Bt) do { __builtin_amdgcn_s_setprio(1); _Pragma("unroll") for (int m = 0; m < 4; ++m) _Pragma("unroll") for (int n = 0; n < 2; ++n) _Pragma("unroll") for (int k = 0; k < 2; ++k) \
;         acc[ai][bj][m][n] = __builtin_amdgcn_mfma_f32_16x16x32_bf16(Bt[n][k], At[m][k], acc[ai][bj][m][n], 0, 0, 0); __builtin_amdgcn_s_setprio(0); } while (0)
; #define PG8_WAIT_V(n) asm volatile("s_waitcnt vmcnt(" #n ")" ::: "memory")
; #define PG8_WAIT_L(n) asm volatile("s_waitcnt lgkmcnt(" #n ")" ::: "memory")
; #define PG8_BAR __builtin_amdgcn_s_barrier()
; #define PG8_SCHED __builtin_amdgcn_sched_barrier(0)
; template <class Epi, class Sched, bool ALIGN_EPI = false, bool SP2 = false>
; __device__ __forceinline__ void gemm_phase(PG8_LAS unsigned char* lds, const Gemm g, const Sched& S, const Epi& E) {
;     ...
;             PG8_WAIT_V(8); PG8_WAIT_L(0); PG8_BAR; PG8_MMA(0, 0, At, B0); PG8_MMA(0, 1, At, B1); PG8_BAR; PG8_SCHED;
;             PG8_LDA(At, 1, 1); PG8_STAGE(PG8_SB(1, 0), b3, voffB); PG8_STAGE(PG8_SB(1, 1), b3 + hstep, voffB); PG8_STAGE(PG8_SA(1, 0), a3, voffA);
;             PG8_WAIT_V(8); PG8_WAIT_L(0); PG8_BAR; PG8_MMA(1, 0, At, B0); PG8_MMA(1, 1, At, B1); PG8_BAR; PG8_SCHED;
	s_setprio 1
	s_waitcnt lgkmcnt(0)
	v_mfma_f32_16x16x32_bf16 v[124:127], v[128:131], v[160:163], v[124:127]
	v_mfma_f32_16x16x32_bf16 v[120:123], v[136:139], v[160:163], v[120:123]
	v_mfma_f32_16x16x32_bf16 v[108:111], v[128:131], v[188:191], v[108:111]
	v_mfma_f32_16x16x32_bf16 v[104:107], v[136:139], v[188:191], v[104:107]
	v_mfma_f32_16x16x32_bf16 v[92:95], v[128:131], v[230:233], v[92:95]
	v_mfma_f32_16x16x32_bf16 v[88:91], v[136:139], v[230:233], v[88:91]
	v_mfma_f32_16x16x32_bf16 v[76:79], v[128:131], v[238:241], v[76:79]
	v_mfma_f32_16x16x32_bf16 v[72:75], v[136:139], v[238:241], v[72:75]
	v_mfma_f32_16x16x32_bf16 v[124:127], v[132:135], v[164:167], v[124:127]
	v_mfma_f32_16x16x32_bf16 v[120:123], v[140:143], v[164:167], v[120:123]
	v_mfma_f32_16x16x32_bf16 v[108:111], v[132:135], v[226:229], v[108:111]
	v_mfma_f32_16x16x32_bf16 v[104:107], v[140:143], v[226:229], v[104:107]
	v_mfma_f32_16x16x32_bf16 v[92:95], v[132:135], v[234:237], v[92:95]
	v_mfma_f32_16x16x32_bf16 v[88:91], v[140:143], v[234:237], v[88:91]
	v_mfma_f32_16x16x32_bf16 v[76:79], v[132:135], v[242:245], v[76:79]
	v_mfma_f32_16x16x32_bf16 v[72:75], v[140:143], v[242:245], v[72:75]
	s_setprio 0
	s_setprio 1
	v_mfma_f32_16x16x32_bf16 v[116:119], v[144:147], v[160:163], v[116:119]
	v_mfma_f32_16x16x32_bf16 v[112:115], v[152:155], v[160:163], v[112:115]
	v_mfma_f32_16x16x32_bf16 v[100:103], v[144:147], v[188:191], v[100:103]
	v_mfma_f32_16x16x32_bf16 v[96:99], v[152:155], v[188:191], v[96:99]
	v_mfma_f32_16x16x32_bf16 v[84:87], v[144:147], v[230:233], v[84:87]
	v_mfma_f32_16x16x32_bf16 v[80:83], v[152:155], v[230:233], v[80:83]
	v_mfma_f32_16x16x32_bf16 v[68:71], v[144:147], v[238:241], v[68:71]
	v_mfma_f32_16x16x32_bf16 v[64:67], v[152:155], v[238:241], v[64:67]
	v_mfma_f32_16x16x32_bf16 v[116:119], v[148:151], v[164:167], v[116:119]
	v_mfma_f32_16x16x32_bf16 v[112:115], v[156:159], v[164:167], v[112:115]
	v_mfma_f32_16x16x32_bf16 v[100:103], v[148:151], v[226:229], v[100:103]
	v_mfma_f32_16x16x32_bf16 v[96:99], v[156:159], v[226:229], v[96:99]
	v_mfma_f32_16x16x32_bf16 v[84:87], v[148:151], v[234:237], v[84:87]
	v_mfma_f32_16x16x32_bf16 v[80:83], v[156:159], v[234:237], v[80:83]
	v_mfma_f32_16x16x32_bf16 v[68:71], v[148:151], v[242:245], v[68:71]
	v_mfma_f32_16x16x32_bf16 v[64:67], v[156:159], v[242:245], v[64:67]
	s_setprio 0
	s_barrier
	s_add_i32 s0, s56, s38
	v_lshl_add_u64 v[192:193], v[192:193], 0, s[22:23]
	s_mov_b32 m0, s0
	ds_read_b128 v[160:163], v220 offset:49152
	ds_read_b128 v[164:167], v220 offset:50176
	ds_read_b128 v[188:191], v220 offset:51200
	ds_read_b128 v[226:229], v220 offset:52224
	ds_read_b128 v[230:233], v220 offset:53248
	ds_read_b128 v[234:237], v220 offset:54272
	ds_read_b128 v[238:241], v220 offset:55296
	ds_read_b128 v[242:245], v220 offset:56320
	global_load_lds_dwordx4 v[192:193], off
	s_add_i32 m0, s0, 0x2000
	s_add_u32 s0, s34, 0xb0080
	v_lshl_add_u64 v[192:193], v[246:247], 0, s[22:23]
	s_addc_u32 s1, s35, 0
	s_add_i32 s34, s57, s38
	global_load_lds_dwordx4 v[192:193], off
	v_lshl_add_u64 v[192:193], s[0:1], 0, v[174:175]
	s_mov_b32 m0, s34
	s_nop 0
	global_load_lds_dwordx4 v[192:193], off
	v_lshl_add_u64 v[192:193], s[0:1], 0, v[178:179]
	s_add_i32 m0, s34, 0x2000
	s_nop 0
	global_load_lds_dwordx4 v[192:193], off
	s_waitcnt vmcnt(4)
	s_waitcnt lgkmcnt(0)
	s_barrier
	s_setprio 1
	s_waitcnt lgkmcnt(0)
	v_mfma_f32_16x16x32_bf16 v[60:63], v[128:131], v[160:163], v[60:63]
	v_mfma_f32_16x16x32_bf16 v[56:59], v[136:139], v[160:163], v[56:59]
	v_mfma_f32_16x16x32_bf16 v[44:47], v[128:131], v[188:191], v[44:47]
	v_mfma_f32_16x16x32_bf16 v[40:43], v[136:139], v[188:191], v[40:43]
	v_mfma_f32_16x16x32_bf16 v[28:31], v[128:131], v[230:233], v[28:31]
	v_mfma_f32_16x16x32_bf16 v[24:27], v[136:139], v[230:233], v[24:27]
	v_mfma_f32_16x16x32_bf16 v[12:15], v[128:131], v[238:241], v[12:15]
	v_mfma_f32_16x16x32_bf16 v[8:11], v[136:139], v[238:241], v[8:11]
	v_mfma_f32_16x16x32_bf16 v[60:63], v[132:135], v[164:167], v[60:63]
	v_mfma_f32_16x16x32_bf16 v[56:59], v[140:143], v[164:167], v[56:59]
	v_mfma_f32_16x16x32_bf16 v[44:47], v[132:135], v[226:229], v[44:47]
	v_mfma_f32_16x16x32_bf16 v[40:43], v[140:143], v[226:229], v[40:43]
	v_mfma_f32_16x16x32_bf16 v[28:31], v[132:135], v[234:237], v[28:31]
	v_mfma_f32_16x16x32_bf16 v[24:27], v[140:143], v[234:237], v[24:27]
	v_mfma_f32_16x16x32_bf16 v[12:15], v[132:135], v[242:245], v[12:15]
	v_mfma_f32_16x16x32_bf16 v[8:11], v[140:143], v[242:245], v[8:11]
	s_setprio 0
	s_setprio 1
	v_mfma_f32_16x16x32_bf16 v[52:55], v[144:147], v[160:163], v[52:55]
	v_mfma_f32_16x16x32_bf16 v[48:51], v[152:155], v[160:163], v[48:51]
	v_mfma_f32_16x16x32_bf16 v[36:39], v[144:147], v[188:191], v[36:39]
	v_mfma_f32_16x16x32_bf16 v[32:35], v[152:155], v[188:191], v[32:35]
	v_mfma_f32_16x16x32_bf16 v[20:23], v[144:147], v[230:233], v[20:23]
	v_mfma_f32_16x16x32_bf16 v[16:19], v[152:155], v[230:233], v[16:19]
	v_mfma_f32_16x16x32_bf16 v[4:7], v[144:147], v[238:241], v[4:7]
	v_mfma_f32_16x16x32_bf16 v[0:3], v[152:155], v[238:241], v[0:3]
	v_mfma_f32_16x16x32_bf16 v[52:55], v[148:151], v[164:167], v[52:55]
	v_mfma_f32_16x16x32_bf16 v[48:51], v[156:159], v[164:167], v[48:51]
	v_mfma_f32_16x16x32_bf16 v[36:39], v[148:151], v[226:229], v[36:39]
	v_mfma_f32_16x16x32_bf16 v[32:35], v[156:159], v[226:229], v[32:35]
	v_mfma_f32_16x16x32_bf16 v[20:23], v[148:151], v[234:237], v[20:23]
	v_mfma_f32_16x16x32_bf16 v[16:19], v[156:159], v[234:237], v[16:19]
	v_mfma_f32_16x16x32_bf16 v[4:7], v[148:151], v[242:245], v[4:7]
	v_mfma_f32_16x16x32_bf16 v[0:3], v[156:159], v[242:245], v[0:3]
	s_setprio 0
	s_barrier
	s_add_i32 s55, s55, 2
	s_add_u32 s33, s33, 0x100
	s_addc_u32 s54, s54, 0
	s_cmp_gt_u32 s55, 41
	s_mov_b64 s[0:1], s[30:31]
	s_cbranch_scc0 .LBB0_232
	s_and_b64 vcc, exec, s[24:25]
	s_cbranch_vccz .LBB0_235
	s_barrier

; #define PG8_STAGE(bufoff, gbase, voff) do { _Pragma("unroll") for (int _i = 0; _i < 2; ++_i) \
;         __builtin_amdgcn_global_load_lds((const unsigned*)((const char*)(gbase) + (voff)[_i]), (PG8_LAS unsigned*)(lds + (bufoff) + ldsw + _i * 8192), 16, 0, 0); } while (0)
; #define PG8_LDA(dst, b, h) do { _Pragma("unroll") for (int m = 0; m < 4; ++m) _Pragma("unroll") for (int k = 0; k < 2; ++k) dst[m][k] = *(const PG8_LAS bf16x8*)(lds + PG8_SA(b, h) + aoff + m * 2048 + k * 1024); } while (0)
; #define PG8_LDB(dst, b, h) do { _Pragma("unroll") for (int n = 0; n < 2; ++n) _Pragma("unroll") for (int k = 0; k < 2; ++k) dst[n][k] = *(const PG8_LAS bf16x8*)(lds + PG8_SB(b, h) + boff + n * 2048 + k * 1024); } while (0)
; #define PG8_MMA(ai, bj, At, Bt) do { __builtin_amdgcn_s_setprio(1); _Pragma("unroll") for (int m = 0; m < 4; ++m) _Pragma("unroll") for (int n = 0; n < 2; ++n) _Pragma("unroll") for (int k = 0; k < 2; ++k) \
;         acc[ai][bj][m][n] = __builtin_amdgcn_mfma_f32_16x16x32_bf16(Bt[n][k], At[m][k], acc[ai][bj][m][n], 0, 0, 0); __builtin_amdgcn_s_setprio(0); } while (0)
; #define PG8_WAIT_V(n) asm volatile("s_waitcnt vmcnt(" #n ")" ::: "memory")
; #define PG8_WAIT_L(n) asm volatile("s_waitcnt lgkmcnt(" #n ")" ::: "memory")
; #define PG8_BAR __builtin_amdgcn_s_barrier()
; #define PG8_SCHED __builtin_amdgcn_sched_barrier(0)
; template <class Epi, class Sched, bool ALIGN_EPI = false, bool SP2 = false>
; __device__ __forceinline__ void gemm_phase(PG8_LAS unsigned char* lds, const Gemm g, const Sched& S, const Epi& E) {
;     ...
;             PG8_LDB(B0, 0, 0); PG8_LDB(B1, 0, 1); PG8_SCHED; PG8_LDA(At, 0, 0); PG8_STAGE(PG8_SA(1, 1), a1 + hstep, voffA);
;             PG8_WAIT_V(8); PG8_WAIT_L(0); PG8_BAR; PG8_MMA(0, 0, At, B0); PG8_MMA(0, 1, At, B1); PG8_BAR; PG8_SCHED;
;             PG8_LDA(At, 0, 1); PG8_STAGE(PG8_SB(0, 0), b2, voffB); PG8_STAGE(PG8_SB(0, 1), b2 + hstep, voffB); PG8_STAGE(PG8_SA(0, 0), a2, voffA);
.LBB0_369:
	ds_read_b128 v[128:131], v169
	ds_read_b128 v[150:153], v169 offset:1024
	ds_read_b128 v[154:157], v169 offset:2048
	ds_read_b128 v[158:161], v169 offset:3072
	ds_read_b128 v[176:179], v172
	ds_read_b128 v[180:183], v172 offset:1024
	ds_read_b128 v[184:187], v172 offset:2048
	ds_read_b128 v[188:191], v172 offset:3072
	s_add_u32 s36, s0, 0xfffc0080
	s_addc_u32 s37, s1, -1
	s_cmp_eq_u32 s53, 12
	s_cselect_b32 s39, s7, s37
	s_cselect_b32 s38, s27, s36
	s_cselect_b32 s37, s25, s52
	s_cselect_b32 s36, s33, s51
	v_lshl_add_u64 v[162:163], s[0:1], 0, v[142:143]
	s_add_i32 m0, s35, 0xc000
	ds_read_b128 v[202:205], v173
	ds_read_b128 v[206:209], v173 offset:1024
	ds_read_b128 v[210:213], v173 offset:2048
	ds_read_b128 v[214:217], v173 offset:3072
	ds_read_b128 v[218:221], v173 offset:4096
	ds_read_b128 v[222:225], v173 offset:5120
	ds_read_b128 v[226:229], v173 offset:6144
	ds_read_b128 v[230:233], v173 offset:7168
	global_load_lds_dwordx4 v[162:163], off
	v_lshl_add_u64 v[162:163], s[0:1], 0, v[144:145]
	s_add_i32 m0, s35, 0xe000
	s_nop 0
	global_load_lds_dwordx4 v[162:163], off
	s_add_u32 s100, s0, 0xfffc0000
	s_addc_u32 s101, s1, -1
	v_lshl_add_u64 v[162:163], s[100:101], 0, v[142:143]
	s_add_i32 m0, s35, 0x8000
	s_nop 0
	global_load_lds_dwordx4 v[162:163], off
	v_lshl_add_u64 v[162:163], s[100:101], 0, v[144:145]
	s_add_i32 m0, s35, 0xa000
	s_nop 0
	global_load_lds_dwordx4 v[162:163], off
	s_waitcnt vmcnt(8)
	s_waitcnt lgkmcnt(0)
	s_barrier
	s_setprio 1
	s_waitcnt lgkmcnt(0)
	v_mfma_f32_16x16x32_bf16 v[124:127], v[128:131], v[202:205], v[124:127]
	v_mfma_f32_16x16x32_bf16 v[120:123], v[154:157], v[202:205], v[120:123]
	v_mfma_f32_16x16x32_bf16 v[108:111], v[128:131], v[210:213], v[108:111]
	v_mfma_f32_16x16x32_bf16 v[104:107], v[154:157], v[210:213], v[104:107]
	v_mfma_f32_16x16x32_bf16 v[92:95], v[128:131], v[218:221], v[92:95]
	v_mfma_f32_16x16x32_bf16 v[88:91], v[154:157], v[218:221], v[88:91]
	v_mfma_f32_16x16x32_bf16 v[76:79], v[128:131], v[226:229], v[76:79]
	v_mfma_f32_16x16x32_bf16 v[72:75], v[154:157], v[226:229], v[72:75]
	v_mfma_f32_16x16x32_bf16 v[124:127], v[150:153], v[206:209], v[124:127]
	v_mfma_f32_16x16x32_bf16 v[120:123], v[158:161], v[206:209], v[120:123]
	v_mfma_f32_16x16x32_bf16 v[108:111], v[150:153], v[214:217], v[108:111]
	v_mfma_f32_16x16x32_bf16 v[104:107], v[158:161], v[214:217], v[104:107]
	v_mfma_f32_16x16x32_bf16 v[92:95], v[150:153], v[222:225], v[92:95]
	v_mfma_f32_16x16x32_bf16 v[88:91], v[158:161], v[222:225], v[88:91]
	v_mfma_f32_16x16x32_bf16 v[76:79], v[150:153], v[230:233], v[76:79]
	v_mfma_f32_16x16x32_bf16 v[72:75], v[158:161], v[230:233], v[72:75]
	s_setprio 0
	s_setprio 1
	v_mfma_f32_16x16x32_bf16 v[116:119], v[176:179], v[202:205], v[116:119]
	v_mfma_f32_16x16x32_bf16 v[112:115], v[184:187], v[202:205], v[112:115]
	v_mfma_f32_16x16x32_bf16 v[100:103], v[176:179], v[210:213], v[100:103]
	v_mfma_f32_16x16x32_bf16 v[96:99], v[184:187], v[210:213], v[96:99]
	v_mfma_f32_16x16x32_bf16 v[84:87], v[176:179], v[218:221], v[84:87]
	v_mfma_f32_16x16x32_bf16 v[80:83], v[184:187], v[218:221], v[80:83]
	v_mfma_f32_16x16x32_bf16 v[68:71], v[176:179], v[226:229], v[68:71]
	v_mfma_f32_16x16x32_bf16 v[64:67], v[184:187], v[226:229], v[64:67]
	v_mfma_f32_16x16x32_bf16 v[116:119], v[180:183], v[206:209], v[116:119]
	v_mfma_f32_16x16x32_bf16 v[112:115], v[188:191], v[206:209], v[112:115]
	v_mfma_f32_16x16x32_bf16 v[100:103], v[180:183], v[214:217], v[100:103]
	v_mfma_f32_16x16x32_bf16 v[96:99], v[188:191], v[214:217], v[96:99]
	v_mfma_f32_16x16x32_bf16 v[84:87], v[180:183], v[222:225], v[84:87]
	v_mfma_f32_16x16x32_bf16 v[80:83], v[188:191], v[222:225], v[80:83]
	v_mfma_f32_16x16x32_bf16 v[68:71], v[180:183], v[230:233], v[68:71]
	v_mfma_f32_16x16x32_bf16 v[64:67], v[188:191], v[230:233], v[64:67]
	s_setprio 0
	s_barrier
	s_add_i32 s54, s49, s40
	v_lshl_add_u64 v[162:163], s[36:37], 0, v[134:135]
	s_mov_b32 m0, s54
	ds_read_b128 v[202:205], v173 offset:16384
	ds_read_b128 v[206:209], v173 offset:17408
	ds_read_b128 v[210:213], v173 offset:18432
	ds_read_b128 v[214:217], v173 offset:19456
	ds_read_b128 v[218:221], v173 offset:20480
	ds_read_b128 v[222:225], v173 offset:21504
	ds_read_b128 v[226:229], v173 offset:22528
	ds_read_b128 v[230:233], v173 offset:23552
	global_load_lds_dwordx4 v[162:163], off
	s_add_i32 m0, s54, 0x2000
	s_add_u32 s54, s36, 0x40000
	v_lshl_add_u64 v[192:193], s[36:37], 0, v[138:139]
	s_addc_u32 s55, s37, 0
	s_add_i32 s56, s50, s40
	global_load_lds_dwordx4 v[192:193], off
	v_lshl_add_u64 v[196:197], s[54:55], 0, v[134:135]
	s_mov_b32 m0, s56
	v_lshl_add_u64 v[234:235], s[38:39], 0, v[136:137]
	global_load_lds_dwordx4 v[196:197], off
	v_lshl_add_u64 v[196:197], s[54:55], 0, v[138:139]
	s_add_i32 m0, s56, 0x2000
	s_nop 0
	global_load_lds_dwordx4 v[196:197], off
	s_waitcnt vmcnt(4)
	s_waitcnt lgkmcnt(0)
	s_barrier
; #define PG8_STAGE(bufoff, gbase, voff) do { _Pragma("unroll") for (int _i = 0; _i < 2; ++_i) \
;         __builtin_amdgcn_global_load_lds((const unsigned*)((const char*)(gbase) + (voff)[_i]), (PG8_LAS unsigned*)(lds + (bufoff) + ldsw + _i * 8192), 16, 0, 0); } while (0)
; #define PG8_LDA(dst, b, h) do { _Pragma("unroll") for (int m = 0; m < 4; ++m) _Pragma("unroll") for (int k = 0; k < 2; ++k) dst[m][k] = *(const PG8_LAS bf16x8*)(lds + PG8_SA(b, h) + aoff + m * 2048 + k * 1024); } while (0)
; #define PG8_LDB(dst, b, h) do { _Pragma("unroll") for (int n = 0; n < 2; ++n) _Pragma("unroll") for (int k = 0; k < 2; ++k) dst[n][k] = *(const PG8_LAS bf16x8*)(lds + PG8_SB(b, h) + boff + n * 2048 + k * 1024); } while (0)
; #define PG8_MMA(ai, bj, At, Bt) do { __builtin_amdgcn_s_setprio(1); _Pragma("unroll") for (int m = 0; m < 4; ++m) _Pragma("unroll") for (int n = 0; n < 2; ++n) _Pragma("unroll") for (int k = 0; k < 2; ++k) \
;         acc[ai][bj][m][n] = __builtin_amdgcn_mfma_f32_16x16x32_bf16(Bt[n][k], At[m][k], acc[ai][bj][m][n], 0, 0, 0); __builtin_amdgcn_s_setprio(0); } while (0)
; #define PG8_WAIT_V(n) asm volatile("s_waitcnt vmcnt(" #n ")" ::: "memory")
; #define PG8_WAIT_L(n) asm volatile("s_waitcnt lgkmcnt(" #n ")" ::: "memory")
; #define PG8_BAR __builtin_amdgcn_s_barrier()
; #define PG8_SCHED __builtin_amdgcn_sched_barrier(0)
; template <class Epi, class Sched, bool ALIGN_EPI = false, bool SP2 = false>
; __device__ __forceinline__ void gemm_phase(PG8_LAS unsigned char* lds, const Gemm g, const Sched& S, const Epi& E) {
;     ...
;             PG8_WAIT_V(8); PG8_WAIT_L(0); PG8_BAR; PG8_MMA(1, 0, At, B0); PG8_MMA(1, 1, At, B1); PG8_BAR; PG8_SCHED;
;             PG8_LDB(B0, 1, 0); PG8_LDB(B1, 1, 1); PG8_SCHED; PG8_LDA(At, 1, 0); PG8_STAGE(PG8_SA(0, 1), a2 + hstep, voffA);
;             PG8_WAIT_V(8); PG8_WAIT_L(0); PG8_BAR; PG8_MMA(0, 0, At, B0); PG8_MMA(0, 1, At, B1); PG8_BAR; PG8_SCHED;
	s_setprio 1
	s_waitcnt lgkmcnt(0)
	v_mfma_f32_16x16x32_bf16 v[60:63], v[128:131], v[202:205], v[60:63]
	v_mfma_f32_16x16x32_bf16 v[56:59], v[154:157], v[202:205], v[56:59]
	v_mfma_f32_16x16x32_bf16 v[44:47], v[128:131], v[210:213], v[44:47]
	v_mfma_f32_16x16x32_bf16 v[40:43], v[154:157], v[210:213], v[40:43]
	v_mfma_f32_16x16x32_bf16 v[28:31], v[128:131], v[218:221], v[28:31]
	v_mfma_f32_16x16x32_bf16 v[24:27], v[154:157], v[218:221], v[24:27]
	v_mfma_f32_16x16x32_bf16 v[12:15], v[128:131], v[226:229], v[12:15]
	v_mfma_f32_16x16x32_bf16 v[8:11], v[154:157], v[226:229], v[8:11]
	v_mfma_f32_16x16x32_bf16 v[60:63], v[150:153], v[206:209], v[60:63]
	v_mfma_f32_16x16x32_bf16 v[56:59], v[158:161], v[206:209], v[56:59]
	v_mfma_f32_16x16x32_bf16 v[44:47], v[150:153], v[214:217], v[44:47]
	v_mfma_f32_16x16x32_bf16 v[40:43], v[158:161], v[214:217], v[40:43]
	v_mfma_f32_16x16x32_bf16 v[28:31], v[150:153], v[222:225], v[28:31]
	v_mfma_f32_16x16x32_bf16 v[24:27], v[158:161], v[222:225], v[24:27]
	v_mfma_f32_16x16x32_bf16 v[12:15], v[150:153], v[230:233], v[12:15]
	v_mfma_f32_16x16x32_bf16 v[8:11], v[158:161], v[230:233], v[8:11]
	s_setprio 0
	s_setprio 1
	v_mfma_f32_16x16x32_bf16 v[52:55], v[176:179], v[202:205], v[52:55]
	v_mfma_f32_16x16x32_bf16 v[48:51], v[184:187], v[202:205], v[48:51]
	v_mfma_f32_16x16x32_bf16 v[36:39], v[176:179], v[210:213], v[36:39]
	v_mfma_f32_16x16x32_bf16 v[32:35], v[184:187], v[210:213], v[32:35]
	v_mfma_f32_16x16x32_bf16 v[20:23], v[176:179], v[218:221], v[20:23]
	v_mfma_f32_16x16x32_bf16 v[16:19], v[184:187], v[218:221], v[16:19]
	v_mfma_f32_16x16x32_bf16 v[4:7], v[176:179], v[226:229], v[4:7]
	v_mfma_f32_16x16x32_bf16 v[0:3], v[184:187], v[226:229], v[0:3]
	v_mfma_f32_16x16x32_bf16 v[52:55], v[180:183], v[206:209], v[52:55]
	v_mfma_f32_16x16x32_bf16 v[48:51], v[188:191], v[206:209], v[48:51]
	v_mfma_f32_16x16x32_bf16 v[36:39], v[180:183], v[214:217], v[36:39]
	v_mfma_f32_16x16x32_bf16 v[32:35], v[188:191], v[214:217], v[32:35]
	v_mfma_f32_16x16x32_bf16 v[20:23], v[180:183], v[222:225], v[20:23]
	v_mfma_f32_16x16x32_bf16 v[16:19], v[188:191], v[222:225], v[16:19]
	v_mfma_f32_16x16x32_bf16 v[4:7], v[180:183], v[230:233], v[4:7]
	v_mfma_f32_16x16x32_bf16 v[0:3], v[188:191], v[230:233], v[0:3]
	s_setprio 0
	s_barrier
	s_add_i32 s54, 0, 0x18000
	v_add_u32_e32 v140, s54, v165
	s_add_i32 s55, 0, 0x1c000
	ds_read_b128 v[128:131], v140
	ds_read_b128 v[150:153], v140 offset:1024
	ds_read_b128 v[154:157], v140 offset:2048
	ds_read_b128 v[158:161], v140 offset:3072
	v_add_u32_e32 v140, s55, v165
	ds_read_b128 v[176:179], v140
	ds_read_b128 v[180:183], v140 offset:1024
	ds_read_b128 v[184:187], v140 offset:2048
	ds_read_b128 v[188:191], v140 offset:3072
	s_add_u32 s38, s38, 0x40000
	s_addc_u32 s39, s39, 0
	s_mov_b32 m0, s42
	v_lshl_add_u64 v[236:237], s[38:39], 0, v[132:133]
	ds_read_b128 v[202:205], v173 offset:32768
	ds_read_b128 v[206:209], v173 offset:33792
	ds_read_b128 v[210:213], v173 offset:34816
	ds_read_b128 v[214:217], v173 offset:35840
	ds_read_b128 v[218:221], v173 offset:36864
	ds_read_b128 v[222:225], v173 offset:37888
	ds_read_b128 v[226:229], v173 offset:38912
	ds_read_b128 v[230:233], v173 offset:39936
	global_load_lds_dwordx4 v[236:237], off
	v_lshl_add_u64 v[236:237], s[38:39], 0, v[136:137]
	s_mov_b32 m0, s43
	s_nop 0
	global_load_lds_dwordx4 v[236:237], off
	s_add_u32 s100, s38, 0xfffc0000
	s_addc_u32 s101, s39, -1
	v_lshl_add_u64 v[236:237], s[100:101], 0, v[132:133]
	s_add_i32 m0, s42, 0xffffc000
	s_nop 0
	global_load_lds_dwordx4 v[236:237], off
	v_lshl_add_u64 v[236:237], s[100:101], 0, v[136:137]
	s_add_i32 m0, s43, 0xffffc000
	s_nop 0
	global_load_lds_dwordx4 v[236:237], off
	s_waitcnt vmcnt(8)
	s_waitcnt lgkmcnt(0)
	s_barrier
; #define PG8_STAGE(bufoff, gbase, voff) do { _Pragma("unroll") for (int _i = 0; _i < 2; ++_i) \
;         __builtin_amdgcn_global_load_lds((const unsigned*)((const char*)(gbase) + (voff)[_i]), (PG8_LAS unsigned*)(lds + (bufoff) + ldsw + _i * 8192), 16, 0, 0); } while (0)
; #define PG8_LDA(dst, b, h) do { _Pragma("unroll") for (int m = 0; m < 4; ++m) _Pragma("unroll") for (int k = 0; k < 2; ++k) dst[m][k] = *(const PG8_LAS bf16x8*)(lds + PG8_SA(b, h) + aoff + m * 2048 + k * 1024); } while (0)
; #define PG8_MMA(ai, bj, At, Bt) do { __builtin_amdgcn_s_setprio(1); _Pragma("unroll") for (int m = 0; m < 4; ++m) _Pragma("unroll") for (int n = 0; n < 2; ++n) _Pragma("unroll") for (int k = 0; k < 2; ++k) \
;         acc[ai][bj][m][n] = __builtin_amdgcn_mfma_f32_16x16x32_bf16(Bt[n][k], At[m][k], acc[ai][bj][m][n], 0, 0, 0); __builtin_amdgcn_s_setprio(0); } while (0)
; #define PG8_WAIT_V(n) asm volatile("s_waitcnt vmcnt(" #n ")" ::: "memory")
; #define PG8_WAIT_L(n) asm volatile("s_waitcnt lgkmcnt(" #n ")" ::: "memory")
; #define PG8_BAR __builtin_amdgcn_s_barrier()
; #define PG8_SCHED __builtin_amdgcn_sched_barrier(0)
; template <class Epi, class Sched, bool ALIGN_EPI = false, bool SP2 = false>
; __device__ __forceinline__ void gemm_phase(PG8_LAS unsigned char* lds, const Gemm g, const Sched& S, const Epi& E) {
;     ...
;             PG8_WAIT_V(8); PG8_WAIT_L(0); PG8_BAR; PG8_MMA(0, 0, At, B0); PG8_MMA(0, 1, At, B1); PG8_BAR; PG8_SCHED;
;             PG8_LDA(At, 1, 1); PG8_STAGE(PG8_SB(1, 0), b3, voffB); PG8_STAGE(PG8_SB(1, 1), b3 + hstep, voffB); PG8_STAGE(PG8_SA(1, 0), a3, voffA);
;             PG8_WAIT_V(8); PG8_WAIT_L(0); PG8_BAR; PG8_MMA(1, 0, At, B0); PG8_MMA(1, 1, At, B1); PG8_BAR; PG8_SCHED;
	s_setprio 1
	s_waitcnt lgkmcnt(0)
	v_mfma_f32_16x16x32_bf16 v[124:127], v[128:131], v[202:205], v[124:127]
	v_mfma_f32_16x16x32_bf16 v[120:123], v[154:157], v[202:205], v[120:123]
	v_mfma_f32_16x16x32_bf16 v[108:111], v[128:131], v[210:213], v[108:111]
	v_mfma_f32_16x16x32_bf16 v[104:107], v[154:157], v[210:213], v[104:107]
	v_mfma_f32_16x16x32_bf16 v[92:95], v[128:131], v[218:221], v[92:95]
	v_mfma_f32_16x16x32_bf16 v[88:91], v[154:157], v[218:221], v[88:91]
	v_mfma_f32_16x16x32_bf16 v[76:79], v[128:131], v[226:229], v[76:79]
	v_mfma_f32_16x16x32_bf16 v[72:75], v[154:157], v[226:229], v[72:75]
	v_mfma_f32_16x16x32_bf16 v[124:127], v[150:153], v[206:209], v[124:127]
	v_mfma_f32_16x16x32_bf16 v[120:123], v[158:161], v[206:209], v[120:123]
	v_mfma_f32_16x16x32_bf16 v[108:111], v[150:153], v[214:217], v[108:111]
	v_mfma_f32_16x16x32_bf16 v[104:107], v[158:161], v[214:217], v[104:107]
	v_mfma_f32_16x16x32_bf16 v[92:95], v[150:153], v[222:225], v[92:95]
	v_mfma_f32_16x16x32_bf16 v[88:91], v[158:161], v[222:225], v[88:91]
	v_mfma_f32_16x16x32_bf16 v[76:79], v[150:153], v[230:233], v[76:79]
	v_mfma_f32_16x16x32_bf16 v[72:75], v[158:161], v[230:233], v[72:75]
	s_setprio 0
	s_setprio 1
	v_mfma_f32_16x16x32_bf16 v[116:119], v[176:179], v[202:205], v[116:119]
	v_mfma_f32_16x16x32_bf16 v[112:115], v[184:187], v[202:205], v[112:115]
	v_mfma_f32_16x16x32_bf16 v[100:103], v[176:179], v[210:213], v[100:103]
	v_mfma_f32_16x16x32_bf16 v[96:99], v[184:187], v[210:213], v[96:99]
	v_mfma_f32_16x16x32_bf16 v[84:87], v[176:179], v[218:221], v[84:87]
	v_mfma_f32_16x16x32_bf16 v[80:83], v[184:187], v[218:221], v[80:83]
	v_mfma_f32_16x16x32_bf16 v[68:71], v[176:179], v[226:229], v[68:71]
	v_mfma_f32_16x16x32_bf16 v[64:67], v[184:187], v[226:229], v[64:67]
	v_mfma_f32_16x16x32_bf16 v[116:119], v[180:183], v[206:209], v[116:119]
	v_mfma_f32_16x16x32_bf16 v[112:115], v[188:191], v[206:209], v[112:115]
	v_mfma_f32_16x16x32_bf16 v[100:103], v[180:183], v[214:217], v[100:103]
	v_mfma_f32_16x16x32_bf16 v[96:99], v[188:191], v[214:217], v[96:99]
	v_mfma_f32_16x16x32_bf16 v[84:87], v[180:183], v[222:225], v[84:87]
	v_mfma_f32_16x16x32_bf16 v[80:83], v[188:191], v[222:225], v[80:83]
	v_mfma_f32_16x16x32_bf16 v[68:71], v[180:183], v[230:233], v[68:71]
	v_mfma_f32_16x16x32_bf16 v[64:67], v[188:191], v[230:233], v[64:67]
	s_setprio 0
	s_barrier
	s_add_i32 s38, s54, s40
	v_lshl_add_u64 v[162:163], v[162:163], 0, s[10:11]
	s_mov_b32 m0, s38
	ds_read_b128 v[202:205], v173 offset:49152
	ds_read_b128 v[206:209], v173 offset:50176
	ds_read_b128 v[210:213], v173 offset:51200
	ds_read_b128 v[214:217], v173 offset:52224
	ds_read_b128 v[218:221], v173 offset:53248
	ds_read_b128 v[222:225], v173 offset:54272
	ds_read_b128 v[226:229], v173 offset:55296
	ds_read_b128 v[230:233], v173 offset:56320
	global_load_lds_dwordx4 v[162:163], off
	s_add_i32 m0, s38, 0x2000
	s_add_u32 s36, s36, 0x40080
	v_lshl_add_u64 v[162:163], v[192:193], 0, s[10:11]
	s_addc_u32 s37, s37, 0
	s_add_i32 s38, s55, s40
	global_load_lds_dwordx4 v[162:163], off
	v_lshl_add_u64 v[162:163], s[36:37], 0, v[134:135]
	s_mov_b32 m0, s38
	s_nop 0
	global_load_lds_dwordx4 v[162:163], off
	v_lshl_add_u64 v[162:163], s[36:37], 0, v[138:139]
	s_add_i32 m0, s38, 0x2000
	s_nop 0
	global_load_lds_dwordx4 v[162:163], off
	s_waitcnt vmcnt(4)
	s_waitcnt lgkmcnt(0)
	s_barrier
	s_setprio 1
	s_waitcnt lgkmcnt(0)
	v_mfma_f32_16x16x32_bf16 v[60:63], v[128:131], v[202:205], v[60:63]
	v_mfma_f32_16x16x32_bf16 v[56:59], v[154:157], v[202:205], v[56:59]
	v_mfma_f32_16x16x32_bf16 v[44:47], v[128:131], v[210:213], v[44:47]
	v_mfma_f32_16x16x32_bf16 v[40:43], v[154:157], v[210:213], v[40:43]
	v_mfma_f32_16x16x32_bf16 v[28:31], v[128:131], v[218:221], v[28:31]
	v_mfma_f32_16x16x32_bf16 v[24:27], v[154:157], v[218:221], v[24:27]
	v_mfma_f32_16x16x32_bf16 v[12:15], v[128:131], v[226:229], v[12:15]
	v_mfma_f32_16x16x32_bf16 v[8:11], v[154:157], v[226:229], v[8:11]
	v_mfma_f32_16x16x32_bf16 v[60:63], v[150:153], v[206:209], v[60:63]
	v_mfma_f32_16x16x32_bf16 v[56:59], v[158:161], v[206:209], v[56:59]
	v_mfma_f32_16x16x32_bf16 v[44:47], v[150:153], v[214:217], v[44:47]
	v_mfma_f32_16x16x32_bf16 v[40:43], v[158:161], v[214:217], v[40:43]
	v_mfma_f32_16x16x32_bf16 v[28:31], v[150:153], v[222:225], v[28:31]
	v_mfma_f32_16x16x32_bf16 v[24:27], v[158:161], v[222:225], v[24:27]
	v_mfma_f32_16x16x32_bf16 v[12:15], v[150:153], v[230:233], v[12:15]
	v_mfma_f32_16x16x32_bf16 v[8:11], v[158:161], v[230:233], v[8:11]
	s_setprio 0
	s_setprio 1
	v_mfma_f32_16x16x32_bf16 v[52:55], v[176:179], v[202:205], v[52:55]
	v_mfma_f32_16x16x32_bf16 v[48:51], v[184:187], v[202:205], v[48:51]
	v_mfma_f32_16x16x32_bf16 v[36:39], v[176:179], v[210:213], v[36:39]
	v_mfma_f32_16x16x32_bf16 v[32:35], v[184:187], v[210:213], v[32:35]
	v_mfma_f32_16x16x32_bf16 v[20:23], v[176:179], v[218:221], v[20:23]
	v_mfma_f32_16x16x32_bf16 v[16:19], v[184:187], v[218:221], v[16:19]
	v_mfma_f32_16x16x32_bf16 v[4:7], v[176:179], v[226:229], v[4:7]
	v_mfma_f32_16x16x32_bf16 v[0:3], v[184:187], v[226:229], v[0:3]
	v_mfma_f32_16x16x32_bf16 v[52:55], v[180:183], v[206:209], v[52:55]
	v_mfma_f32_16x16x32_bf16 v[48:51], v[188:191], v[206:209], v[48:51]
	v_mfma_f32_16x16x32_bf16 v[36:39], v[180:183], v[214:217], v[36:39]
	v_mfma_f32_16x16x32_bf16 v[32:35], v[188:191], v[214:217], v[32:35]
	v_mfma_f32_16x16x32_bf16 v[20:23], v[180:183], v[222:225], v[20:23]
	v_mfma_f32_16x16x32_bf16 v[16:19], v[188:191], v[222:225], v[16:19]
	v_mfma_f32_16x16x32_bf16 v[4:7], v[180:183], v[230:233], v[4:7]
	v_mfma_f32_16x16x32_bf16 v[0:3], v[188:191], v[230:233], v[0:3]
	s_setprio 0
	s_barrier
	s_add_i32 s53, s53, 2
	s_add_u32 s0, s0, 0x100
	s_addc_u32 s1, s1, 0
	s_add_u32 s51, s51, 0x100
	s_addc_u32 s52, s52, 0
	s_cmp_gt_u32 s53, 13
	s_cbranch_scc0 .LBB0_369
	s_and_b64 vcc, exec, s[12:13]
	s_cbranch_vccz .LBB0_372
	s_barrier

; #define PG8_STAGE(bufoff, gbase, voff) do { _Pragma("unroll") for (int _i = 0; _i < 2; ++_i) \
;         __builtin_amdgcn_global_load_lds((const unsigned*)((const char*)(gbase) + (voff)[_i]), (PG8_LAS unsigned*)(lds + (bufoff) + ldsw + _i * 8192), 16, 0, 0); } while (0)
; #define PG8_LDA(dst, b, h) do { _Pragma("unroll") for (int m = 0; m < 4; ++m) _Pragma("unroll") for (int k = 0; k < 2; ++k) dst[m][k] = *(const PG8_LAS bf16x8*)(lds + PG8_SA(b, h) + aoff + m * 2048 + k * 1024); } while (0)
; #define PG8_LDB(dst, b, h) do { _Pragma("unroll") for (int n = 0; n < 2; ++n) _Pragma("unroll") for (int k = 0; k < 2; ++k) dst[n][k] = *(const PG8_LAS bf16x8*)(lds + PG8_SB(b, h) + boff + n * 2048 + k * 1024); } while (0)
; #define PG8_MMA(ai, bj, At, Bt) do { __builtin_amdgcn_s_setprio(1); _Pragma("unroll") for (int m = 0; m < 4; ++m) _Pragma("unroll") for (int n = 0; n < 2; ++n) _Pragma("unroll") for (int k = 0; k < 2; ++k) \
;         acc[ai][bj][m][n] = __builtin_amdgcn_mfma_f32_16x16x32_bf16(Bt[n][k], At[m][k], acc[ai][bj][m][n], 0, 0, 0); __builtin_amdgcn_s_setprio(0); } while (0)
; #define PG8_WAIT_V(n) asm volatile("s_waitcnt vmcnt(" #n ")" ::: "memory")
; #define PG8_WAIT_L(n) asm volatile("s_waitcnt lgkmcnt(" #n ")" ::: "memory")
; #define PG8_BAR __builtin_amdgcn_s_barrier()
; #define PG8_SCHED __builtin_amdgcn_sched_barrier(0)
; template <class Epi, class Sched, bool ALIGN_EPI = false, bool SP2 = false>
; __device__ __forceinline__ void gemm_phase(PG8_LAS unsigned char* lds, const Gemm g, const Sched& S, const Epi& E) {
;     ...
;             PG8_LDB(B0, 0, 0); PG8_LDB(B1, 0, 1); PG8_SCHED; PG8_LDA(At, 0, 0); PG8_STAGE(PG8_SA(1, 1), a1 + hstep, voffA);
;             PG8_WAIT_V(8); PG8_WAIT_L(0); PG8_BAR; PG8_MMA(0, 0, At, B0); PG8_MMA(0, 1, At, B1); PG8_BAR; PG8_SCHED;
;             PG8_LDA(At, 0, 1); PG8_STAGE(PG8_SB(0, 0), b2, voffB); PG8_STAGE(PG8_SB(0, 1), b2 + hstep, voffB); PG8_STAGE(PG8_SA(0, 0), a2, voffA);
.LBB0_699:
	ds_read_b128 v[128:131], v222
	ds_read_b128 v[132:135], v222 offset:1024
	ds_read_b128 v[136:139], v222 offset:2048
	ds_read_b128 v[140:143], v222 offset:3072
	ds_read_b128 v[144:147], v223
	ds_read_b128 v[148:151], v223 offset:1024
	ds_read_b128 v[152:155], v223 offset:2048
	ds_read_b128 v[156:159], v223 offset:3072
	s_add_u32 s34, s0, 0xfffc0080
	s_addc_u32 s35, s1, -1
	s_cmp_eq_u32 s65, 12
	s_cselect_b32 s37, s25, s35
	s_cselect_b32 s36, s31, s34
	s_cselect_b32 s35, s23, s63
	s_cselect_b32 s34, s33, s62
	v_lshl_add_u64 v[244:245], s[0:1], 0, v[182:183]
	s_add_i32 m0, s39, 0xc000
	ds_read_b128 v[160:163], v224
	ds_read_b128 v[164:167], v224 offset:1024
	ds_read_b128 v[190:193], v224 offset:2048
	ds_read_b128 v[194:197], v224 offset:3072
	ds_read_b128 v[228:231], v224 offset:4096
	ds_read_b128 v[232:235], v224 offset:5120
	ds_read_b128 v[236:239], v224 offset:6144
	ds_read_b128 v[240:243], v224 offset:7168
	global_load_lds_dwordx4 v[244:245], off
	v_lshl_add_u64 v[244:245], s[0:1], 0, v[184:185]
	s_add_i32 m0, s39, 0xe000
	s_nop 0
	global_load_lds_dwordx4 v[244:245], off
	s_add_u32 s100, s0, 0xfffc0000
	s_addc_u32 s101, s1, -1
	v_lshl_add_u64 v[244:245], s[100:101], 0, v[182:183]
	s_add_i32 m0, s39, 0x8000
	s_nop 0
	global_load_lds_dwordx4 v[244:245], off
	v_lshl_add_u64 v[244:245], s[100:101], 0, v[184:185]
	s_add_i32 m0, s39, 0xa000
	s_nop 0
	global_load_lds_dwordx4 v[244:245], off
	s_waitcnt vmcnt(8)
	s_waitcnt lgkmcnt(0)
	s_barrier
	s_setprio 1
	s_waitcnt lgkmcnt(0)
	v_mfma_f32_16x16x32_bf16 v[124:127], v[128:131], v[160:163], v[124:127]
	v_mfma_f32_16x16x32_bf16 v[120:123], v[136:139], v[160:163], v[120:123]
	v_mfma_f32_16x16x32_bf16 v[108:111], v[128:131], v[190:193], v[108:111]
	v_mfma_f32_16x16x32_bf16 v[104:107], v[136:139], v[190:193], v[104:107]
	v_mfma_f32_16x16x32_bf16 v[92:95], v[128:131], v[228:231], v[92:95]
	v_mfma_f32_16x16x32_bf16 v[88:91], v[136:139], v[228:231], v[88:91]
	v_mfma_f32_16x16x32_bf16 v[76:79], v[128:131], v[236:239], v[76:79]
	v_mfma_f32_16x16x32_bf16 v[72:75], v[136:139], v[236:239], v[72:75]
	v_mfma_f32_16x16x32_bf16 v[124:127], v[132:135], v[164:167], v[124:127]
	v_mfma_f32_16x16x32_bf16 v[120:123], v[140:143], v[164:167], v[120:123]
	v_mfma_f32_16x16x32_bf16 v[108:111], v[132:135], v[194:197], v[108:111]
	v_mfma_f32_16x16x32_bf16 v[104:107], v[140:143], v[194:197], v[104:107]
	v_mfma_f32_16x16x32_bf16 v[92:95], v[132:135], v[232:235], v[92:95]
	v_mfma_f32_16x16x32_bf16 v[88:91], v[140:143], v[232:235], v[88:91]
	v_mfma_f32_16x16x32_bf16 v[76:79], v[132:135], v[240:243], v[76:79]
	v_mfma_f32_16x16x32_bf16 v[72:75], v[140:143], v[240:243], v[72:75]
	s_setprio 0
	s_setprio 1
	v_mfma_f32_16x16x32_bf16 v[116:119], v[144:147], v[160:163], v[116:119]
	v_mfma_f32_16x16x32_bf16 v[112:115], v[152:155], v[160:163], v[112:115]
	v_mfma_f32_16x16x32_bf16 v[100:103], v[144:147], v[190:193], v[100:103]
	v_mfma_f32_16x16x32_bf16 v[96:99], v[152:155], v[190:193], v[96:99]
	v_mfma_f32_16x16x32_bf16 v[84:87], v[144:147], v[228:231], v[84:87]
	v_mfma_f32_16x16x32_bf16 v[80:83], v[152:155], v[228:231], v[80:83]
	v_mfma_f32_16x16x32_bf16 v[68:71], v[144:147], v[236:239], v[68:71]
	v_mfma_f32_16x16x32_bf16 v[64:67], v[152:155], v[236:239], v[64:67]
	v_mfma_f32_16x16x32_bf16 v[116:119], v[148:151], v[164:167], v[116:119]
	v_mfma_f32_16x16x32_bf16 v[112:115], v[156:159], v[164:167], v[112:115]
	v_mfma_f32_16x16x32_bf16 v[100:103], v[148:151], v[194:197], v[100:103]
	v_mfma_f32_16x16x32_bf16 v[96:99], v[156:159], v[194:197], v[96:99]
	v_mfma_f32_16x16x32_bf16 v[84:87], v[148:151], v[232:235], v[84:87]
	v_mfma_f32_16x16x32_bf16 v[80:83], v[156:159], v[232:235], v[80:83]
	v_mfma_f32_16x16x32_bf16 v[68:71], v[148:151], v[240:243], v[68:71]
	v_mfma_f32_16x16x32_bf16 v[64:67], v[156:159], v[240:243], v[64:67]
	s_setprio 0
	s_barrier
	s_add_i32 s66, s46, s38
	v_lshl_add_u64 v[244:245], s[34:35], 0, v[174:175]
	s_mov_b32 m0, s66
	ds_read_b128 v[160:163], v224 offset:16384
	ds_read_b128 v[164:167], v224 offset:17408
	ds_read_b128 v[190:193], v224 offset:18432
	ds_read_b128 v[194:197], v224 offset:19456
	ds_read_b128 v[228:231], v224 offset:20480
	ds_read_b128 v[232:235], v224 offset:21504
	ds_read_b128 v[236:239], v224 offset:22528
	ds_read_b128 v[240:243], v224 offset:23552
	global_load_lds_dwordx4 v[244:245], off
	s_add_i32 m0, s66, 0x2000
	s_add_u32 s66, s34, 0x40000
	v_lshl_add_u64 v[246:247], s[34:35], 0, v[178:179]
	s_addc_u32 s67, s35, 0
	s_add_i32 s68, s56, s38
	global_load_lds_dwordx4 v[246:247], off
	v_lshl_add_u64 v[248:249], s[66:67], 0, v[174:175]
	s_mov_b32 m0, s68
	v_lshl_add_u64 v[250:251], s[36:37], 0, v[176:177]
	global_load_lds_dwordx4 v[248:249], off
	v_lshl_add_u64 v[248:249], s[66:67], 0, v[178:179]
	s_add_i32 m0, s68, 0x2000
	s_nop 0
	global_load_lds_dwordx4 v[248:249], off
	s_waitcnt vmcnt(4)
	s_waitcnt lgkmcnt(0)
	s_barrier
; #define PG8_STAGE(bufoff, gbase, voff) do { _Pragma("unroll") for (int _i = 0; _i < 2; ++_i) \
;         __builtin_amdgcn_global_load_lds((const unsigned*)((const char*)(gbase) + (voff)[_i]), (PG8_LAS unsigned*)(lds + (bufoff) + ldsw + _i * 8192), 16, 0, 0); } while (0)
; #define PG8_LDA(dst, b, h) do { _Pragma("unroll") for (int m = 0; m < 4; ++m) _Pragma("unroll") for (int k = 0; k < 2; ++k) dst[m][k] = *(const PG8_LAS bf16x8*)(lds + PG8_SA(b, h) + aoff + m * 2048 + k * 1024); } while (0)
; #define PG8_LDB(dst, b, h) do { _Pragma("unroll") for (int n = 0; n < 2; ++n) _Pragma("unroll") for (int k = 0; k < 2; ++k) dst[n][k] = *(const PG8_LAS bf16x8*)(lds + PG8_SB(b, h) + boff + n * 2048 + k * 1024); } while (0)
; #define PG8_MMA(ai, bj, At, Bt) do { __builtin_amdgcn_s_setprio(1); _Pragma("unroll") for (int m = 0; m < 4; ++m) _Pragma("unroll") for (int n = 0; n < 2; ++n) _Pragma("unroll") for (int k = 0; k < 2; ++k) \
;         acc[ai][bj][m][n] = __builtin_amdgcn_mfma_f32_16x16x32_bf16(Bt[n][k], At[m][k], acc[ai][bj][m][n], 0, 0, 0); __builtin_amdgcn_s_setprio(0); } while (0)
; #define PG8_WAIT_V(n) asm volatile("s_waitcnt vmcnt(" #n ")" ::: "memory")
; #define PG8_WAIT_L(n) asm volatile("s_waitcnt lgkmcnt(" #n ")" ::: "memory")
; #define PG8_BAR __builtin_amdgcn_s_barrier()
; #define PG8_SCHED __builtin_amdgcn_sched_barrier(0)
; template <class Epi, class Sched, bool ALIGN_EPI = false, bool SP2 = false>
; __device__ __forceinline__ void gemm_phase(PG8_LAS unsigned char* lds, const Gemm g, const Sched& S, const Epi& E) {
;     ...
;             PG8_WAIT_V(8); PG8_WAIT_L(0); PG8_BAR; PG8_MMA(1, 0, At, B0); PG8_MMA(1, 1, At, B1); PG8_BAR; PG8_SCHED;
;             PG8_LDB(B0, 1, 0); PG8_LDB(B1, 1, 1); PG8_SCHED; PG8_LDA(At, 1, 0); PG8_STAGE(PG8_SA(0, 1), a2 + hstep, voffA);
;             PG8_WAIT_V(8); PG8_WAIT_L(0); PG8_BAR; PG8_MMA(0, 0, At, B0); PG8_MMA(0, 1, At, B1); PG8_BAR; PG8_SCHED;
	s_setprio 1
	s_waitcnt lgkmcnt(0)
	v_mfma_f32_16x16x32_bf16 v[60:63], v[128:131], v[160:163], v[60:63]
	v_mfma_f32_16x16x32_bf16 v[56:59], v[136:139], v[160:163], v[56:59]
	v_mfma_f32_16x16x32_bf16 v[44:47], v[128:131], v[190:193], v[44:47]
	v_mfma_f32_16x16x32_bf16 v[40:43], v[136:139], v[190:193], v[40:43]
	v_mfma_f32_16x16x32_bf16 v[28:31], v[128:131], v[228:231], v[28:31]
	v_mfma_f32_16x16x32_bf16 v[24:27], v[136:139], v[228:231], v[24:27]
	v_mfma_f32_16x16x32_bf16 v[12:15], v[128:131], v[236:239], v[12:15]
	v_mfma_f32_16x16x32_bf16 v[8:11], v[136:139], v[236:239], v[8:11]
	v_mfma_f32_16x16x32_bf16 v[60:63], v[132:135], v[164:167], v[60:63]
	v_mfma_f32_16x16x32_bf16 v[56:59], v[140:143], v[164:167], v[56:59]
	v_mfma_f32_16x16x32_bf16 v[44:47], v[132:135], v[194:197], v[44:47]
	v_mfma_f32_16x16x32_bf16 v[40:43], v[140:143], v[194:197], v[40:43]
	v_mfma_f32_16x16x32_bf16 v[28:31], v[132:135], v[232:235], v[28:31]
	v_mfma_f32_16x16x32_bf16 v[24:27], v[140:143], v[232:235], v[24:27]
	v_mfma_f32_16x16x32_bf16 v[12:15], v[132:135], v[240:243], v[12:15]
	v_mfma_f32_16x16x32_bf16 v[8:11], v[140:143], v[240:243], v[8:11]
	s_setprio 0
	s_setprio 1
	v_mfma_f32_16x16x32_bf16 v[52:55], v[144:147], v[160:163], v[52:55]
	v_mfma_f32_16x16x32_bf16 v[48:51], v[152:155], v[160:163], v[48:51]
	v_mfma_f32_16x16x32_bf16 v[36:39], v[144:147], v[190:193], v[36:39]
	v_mfma_f32_16x16x32_bf16 v[32:35], v[152:155], v[190:193], v[32:35]
	v_mfma_f32_16x16x32_bf16 v[20:23], v[144:147], v[228:231], v[20:23]
	v_mfma_f32_16x16x32_bf16 v[16:19], v[152:155], v[228:231], v[16:19]
	v_mfma_f32_16x16x32_bf16 v[4:7], v[144:147], v[236:239], v[4:7]
	v_mfma_f32_16x16x32_bf16 v[0:3], v[152:155], v[236:239], v[0:3]
	v_mfma_f32_16x16x32_bf16 v[52:55], v[148:151], v[164:167], v[52:55]
	v_mfma_f32_16x16x32_bf16 v[48:51], v[156:159], v[164:167], v[48:51]
	v_mfma_f32_16x16x32_bf16 v[36:39], v[148:151], v[194:197], v[36:39]
	v_mfma_f32_16x16x32_bf16 v[32:35], v[156:159], v[194:197], v[32:35]
	v_mfma_f32_16x16x32_bf16 v[20:23], v[148:151], v[232:235], v[20:23]
	v_mfma_f32_16x16x32_bf16 v[16:19], v[156:159], v[232:235], v[16:19]
	v_mfma_f32_16x16x32_bf16 v[4:7], v[148:151], v[240:243], v[4:7]
	v_mfma_f32_16x16x32_bf16 v[0:3], v[156:159], v[240:243], v[0:3]
	s_setprio 0
	s_barrier
	s_add_i32 s66, 0, 0x18000
	s_add_i32 s67, 0, 0x1c000
	v_add_u32_e32 v140, s66, v204
	v_add_u32_e32 v156, s67, v204
	ds_read_b128 v[128:131], v140
	ds_read_b128 v[132:135], v140 offset:1024
	ds_read_b128 v[136:139], v140 offset:2048
	ds_read_b128 v[140:143], v140 offset:3072
	ds_read_b128 v[144:147], v156
	ds_read_b128 v[148:151], v156 offset:1024
	ds_read_b128 v[152:155], v156 offset:2048
	ds_read_b128 v[156:159], v156 offset:3072
	s_add_u32 s36, s36, 0x40000
	s_addc_u32 s37, s37, 0
	s_mov_b32 m0, s41
	v_lshl_add_u64 v[252:253], s[36:37], 0, v[172:173]
	ds_read_b128 v[160:163], v224 offset:32768
	ds_read_b128 v[164:167], v224 offset:33792
	ds_read_b128 v[190:193], v224 offset:34816
	ds_read_b128 v[194:197], v224 offset:35840
	ds_read_b128 v[228:231], v224 offset:36864
	ds_read_b128 v[232:235], v224 offset:37888
	ds_read_b128 v[236:239], v224 offset:38912
	ds_read_b128 v[240:243], v224 offset:39936
	global_load_lds_dwordx4 v[252:253], off
	v_lshl_add_u64 v[252:253], s[36:37], 0, v[176:177]
	s_mov_b32 m0, s42
	s_nop 0
	global_load_lds_dwordx4 v[252:253], off
	s_add_u32 s100, s36, 0xfffc0000
	s_addc_u32 s101, s37, -1
	v_lshl_add_u64 v[252:253], s[100:101], 0, v[172:173]
	s_add_i32 m0, s41, 0xffffc000
	s_nop 0
	global_load_lds_dwordx4 v[252:253], off
	v_lshl_add_u64 v[252:253], s[100:101], 0, v[176:177]
	s_add_i32 m0, s42, 0xffffc000
	s_nop 0
	global_load_lds_dwordx4 v[252:253], off
	s_waitcnt vmcnt(8)
	s_waitcnt lgkmcnt(0)
	s_barrier
; #define PG8_STAGE(bufoff, gbase, voff) do { _Pragma("unroll") for (int _i = 0; _i < 2; ++_i) \
;         __builtin_amdgcn_global_load_lds((const unsigned*)((const char*)(gbase) + (voff)[_i]), (PG8_LAS unsigned*)(lds + (bufoff) + ldsw + _i * 8192), 16, 0, 0); } while (0)
; #define PG8_LDA(dst, b, h) do { _Pragma("unroll") for (int m = 0; m < 4; ++m) _Pragma("unroll") for (int k = 0; k < 2; ++k) dst[m][k] = *(const PG8_LAS bf16x8*)(lds + PG8_SA(b, h) + aoff + m * 2048 + k * 1024); } while (0)
; #define PG8_MMA(ai, bj, At, Bt) do { __builtin_amdgcn_s_setprio(1); _Pragma("unroll") for (int m = 0; m < 4; ++m) _Pragma("unroll") for (int n = 0; n < 2; ++n) _Pragma("unroll") for (int k = 0; k < 2; ++k) \
;         acc[ai][bj][m][n] = __builtin_amdgcn_mfma_f32_16x16x32_bf16(Bt[n][k], At[m][k], acc[ai][bj][m][n], 0, 0, 0); __builtin_amdgcn_s_setprio(0); } while (0)
; #define PG8_WAIT_V(n) asm volatile("s_waitcnt vmcnt(" #n ")" ::: "memory")
; #define PG8_WAIT_L(n) asm volatile("s_waitcnt lgkmcnt(" #n ")" ::: "memory")
; #define PG8_BAR __builtin_amdgcn_s_barrier()
; #define PG8_SCHED __builtin_amdgcn_sched_barrier(0)
; template <class Epi, class Sched, bool ALIGN_EPI = false, bool SP2 = false>
; __device__ __forceinline__ void gemm_phase(PG8_LAS unsigned char* lds, const Gemm g, const Sched& S, const Epi& E) {
;     ...
;             PG8_WAIT_V(8); PG8_WAIT_L(0); PG8_BAR; PG8_MMA(0, 0, At, B0); PG8_MMA(0, 1, At, B1); PG8_BAR; PG8_SCHED;
;             PG8_LDA(At, 1, 1); PG8_STAGE(PG8_SB(1, 0), b3, voffB); PG8_STAGE(PG8_SB(1, 1), b3 + hstep, voffB); PG8_STAGE(PG8_SA(1, 0), a3, voffA);
;             PG8_WAIT_V(8); PG8_WAIT_L(0); PG8_BAR; PG8_MMA(1, 0, At, B0); PG8_MMA(1, 1, At, B1); PG8_BAR; PG8_SCHED;
	s_setprio 1
	s_waitcnt lgkmcnt(0)
	v_mfma_f32_16x16x32_bf16 v[124:127], v[128:131], v[160:163], v[124:127]
	v_mfma_f32_16x16x32_bf16 v[120:123], v[136:139], v[160:163], v[120:123]
	v_mfma_f32_16x16x32_bf16 v[108:111], v[128:131], v[190:193], v[108:111]
	v_mfma_f32_16x16x32_bf16 v[104:107], v[136:139], v[190:193], v[104:107]
	v_mfma_f32_16x16x32_bf16 v[92:95], v[128:131], v[228:231], v[92:95]
	v_mfma_f32_16x16x32_bf16 v[88:91], v[136:139], v[228:231], v[88:91]
	v_mfma_f32_16x16x32_bf16 v[76:79], v[128:131], v[236:239], v[76:79]
	v_mfma_f32_16x16x32_bf16 v[72:75], v[136:139], v[236:239], v[72:75]
	v_mfma_f32_16x16x32_bf16 v[124:127], v[132:135], v[164:167], v[124:127]
	v_mfma_f32_16x16x32_bf16 v[120:123], v[140:143], v[164:167], v[120:123]
	v_mfma_f32_16x16x32_bf16 v[108:111], v[132:135], v[194:197], v[108:111]
	v_mfma_f32_16x16x32_bf16 v[104:107], v[140:143], v[194:197], v[104:107]
	v_mfma_f32_16x16x32_bf16 v[92:95], v[132:135], v[232:235], v[92:95]
	v_mfma_f32_16x16x32_bf16 v[88:91], v[140:143], v[232:235], v[88:91]
	v_mfma_f32_16x16x32_bf16 v[76:79], v[132:135], v[240:243], v[76:79]
	v_mfma_f32_16x16x32_bf16 v[72:75], v[140:143], v[240:243], v[72:75]
	s_setprio 0
	s_setprio 1
	v_mfma_f32_16x16x32_bf16 v[116:119], v[144:147], v[160:163], v[116:119]
	v_mfma_f32_16x16x32_bf16 v[112:115], v[152:155], v[160:163], v[112:115]
	v_mfma_f32_16x16x32_bf16 v[100:103], v[144:147], v[190:193], v[100:103]
	v_mfma_f32_16x16x32_bf16 v[96:99], v[152:155], v[190:193], v[96:99]
	v_mfma_f32_16x16x32_bf16 v[84:87], v[144:147], v[228:231], v[84:87]
	v_mfma_f32_16x16x32_bf16 v[80:83], v[152:155], v[228:231], v[80:83]
	v_mfma_f32_16x16x32_bf16 v[68:71], v[144:147], v[236:239], v[68:71]
	v_mfma_f32_16x16x32_bf16 v[64:67], v[152:155], v[236:239], v[64:67]
	v_mfma_f32_16x16x32_bf16 v[116:119], v[148:151], v[164:167], v[116:119]
	v_mfma_f32_16x16x32_bf16 v[112:115], v[156:159], v[164:167], v[112:115]
	v_mfma_f32_16x16x32_bf16 v[100:103], v[148:151], v[194:197], v[100:103]
	v_mfma_f32_16x16x32_bf16 v[96:99], v[156:159], v[194:197], v[96:99]
	v_mfma_f32_16x16x32_bf16 v[84:87], v[148:151], v[232:235], v[84:87]
	v_mfma_f32_16x16x32_bf16 v[80:83], v[156:159], v[232:235], v[80:83]
	v_mfma_f32_16x16x32_bf16 v[68:71], v[148:151], v[240:243], v[68:71]
	v_mfma_f32_16x16x32_bf16 v[64:67], v[156:159], v[240:243], v[64:67]
	s_setprio 0
	s_barrier
	s_add_i32 s36, s66, s38
	v_lshl_add_u64 v[244:245], v[244:245], 0, s[16:17]
	s_mov_b32 m0, s36
	ds_read_b128 v[160:163], v224 offset:49152
	ds_read_b128 v[164:167], v224 offset:50176
	ds_read_b128 v[190:193], v224 offset:51200
	ds_read_b128 v[194:197], v224 offset:52224
	ds_read_b128 v[228:231], v224 offset:53248
	ds_read_b128 v[232:235], v224 offset:54272
	ds_read_b128 v[236:239], v224 offset:55296
	ds_read_b128 v[240:243], v224 offset:56320
	global_load_lds_dwordx4 v[244:245], off
	s_add_i32 m0, s36, 0x2000
	s_add_u32 s34, s34, 0x40080
	v_lshl_add_u64 v[244:245], v[246:247], 0, s[16:17]
	s_addc_u32 s35, s35, 0
	s_add_i32 s36, s67, s38
	global_load_lds_dwordx4 v[244:245], off
	v_lshl_add_u64 v[244:245], s[34:35], 0, v[174:175]
	s_mov_b32 m0, s36
	s_nop 0
	global_load_lds_dwordx4 v[244:245], off
	v_lshl_add_u64 v[244:245], s[34:35], 0, v[178:179]
	s_add_i32 m0, s36, 0x2000
	s_nop 0
	global_load_lds_dwordx4 v[244:245], off
	s_waitcnt vmcnt(4)
	s_waitcnt lgkmcnt(0)
	s_barrier
	s_setprio 1
	s_waitcnt lgkmcnt(0)
	v_mfma_f32_16x16x32_bf16 v[60:63], v[128:131], v[160:163], v[60:63]
	v_mfma_f32_16x16x32_bf16 v[56:59], v[136:139], v[160:163], v[56:59]
	v_mfma_f32_16x16x32_bf16 v[44:47], v[128:131], v[190:193], v[44:47]
	v_mfma_f32_16x16x32_bf16 v[40:43], v[136:139], v[190:193], v[40:43]
	v_mfma_f32_16x16x32_bf16 v[28:31], v[128:131], v[228:231], v[28:31]
	v_mfma_f32_16x16x32_bf16 v[24:27], v[136:139], v[228:231], v[24:27]
	v_mfma_f32_16x16x32_bf16 v[12:15], v[128:131], v[236:239], v[12:15]
	v_mfma_f32_16x16x32_bf16 v[8:11], v[136:139], v[236:239], v[8:11]
	v_mfma_f32_16x16x32_bf16 v[60:63], v[132:135], v[164:167], v[60:63]
	v_mfma_f32_16x16x32_bf16 v[56:59], v[140:143], v[164:167], v[56:59]
	v_mfma_f32_16x16x32_bf16 v[44:47], v[132:135], v[194:197], v[44:47]
	v_mfma_f32_16x16x32_bf16 v[40:43], v[140:143], v[194:197], v[40:43]
	v_mfma_f32_16x16x32_bf16 v[28:31], v[132:135], v[232:235], v[28:31]
	v_mfma_f32_16x16x32_bf16 v[24:27], v[140:143], v[232:235], v[24:27]
	v_mfma_f32_16x16x32_bf16 v[12:15], v[132:135], v[240:243], v[12:15]
	v_mfma_f32_16x16x32_bf16 v[8:11], v[140:143], v[240:243], v[8:11]
	s_setprio 0
	s_setprio 1
	v_mfma_f32_16x16x32_bf16 v[52:55], v[144:147], v[160:163], v[52:55]
	v_mfma_f32_16x16x32_bf16 v[48:51], v[152:155], v[160:163], v[48:51]
	v_mfma_f32_16x16x32_bf16 v[36:39], v[144:147], v[190:193], v[36:39]
	v_mfma_f32_16x16x32_bf16 v[32:35], v[152:155], v[190:193], v[32:35]
	v_mfma_f32_16x16x32_bf16 v[20:23], v[144:147], v[228:231], v[20:23]
	v_mfma_f32_16x16x32_bf16 v[16:19], v[152:155], v[228:231], v[16:19]
	v_mfma_f32_16x16x32_bf16 v[4:7], v[144:147], v[236:239], v[4:7]
	v_mfma_f32_16x16x32_bf16 v[0:3], v[152:155], v[236:239], v[0:3]
	v_mfma_f32_16x16x32_bf16 v[52:55], v[148:151], v[164:167], v[52:55]
	v_mfma_f32_16x16x32_bf16 v[48:51], v[156:159], v[164:167], v[48:51]
	v_mfma_f32_16x16x32_bf16 v[36:39], v[148:151], v[194:197], v[36:39]
	v_mfma_f32_16x16x32_bf16 v[32:35], v[156:159], v[194:197], v[32:35]
	v_mfma_f32_16x16x32_bf16 v[20:23], v[148:151], v[232:235], v[20:23]
	v_mfma_f32_16x16x32_bf16 v[16:19], v[156:159], v[232:235], v[16:19]
	v_mfma_f32_16x16x32_bf16 v[4:7], v[148:151], v[240:243], v[4:7]
	v_mfma_f32_16x16x32_bf16 v[0:3], v[156:159], v[240:243], v[0:3]
	s_setprio 0
	s_barrier
	s_add_i32 s65, s65, 2
	s_add_u32 s0, s0, 0x100
	s_addc_u32 s1, s1, 0
	s_add_u32 s62, s62, 0x100
	s_addc_u32 s63, s63, 0
	s_cmp_gt_u32 s65, 13
	s_cbranch_scc0 .LBB0_699
	s_and_b64 vcc, exec, s[18:19]
	s_cbranch_vccz .LBB0_702
	s_barrier

; #define PG8_STAGE(bufoff, gbase, voff) do { _Pragma("unroll") for (int _i = 0; _i < 2; ++_i) \
;         __builtin_amdgcn_global_load_lds((const unsigned*)((const char*)(gbase) + (voff)[_i]), (PG8_LAS unsigned*)(lds + (bufoff) + ldsw + _i * 8192), 16, 0, 0); } while (0)
; #define PG8_LDA(dst, b, h) do { _Pragma("unroll") for (int m = 0; m < 4; ++m) _Pragma("unroll") for (int k = 0; k < 2; ++k) dst[m][k] = *(const PG8_LAS bf16x8*)(lds + PG8_SA(b, h) + aoff + m * 2048 + k * 1024); } while (0)
; #define PG8_LDB(dst, b, h) do { _Pragma("unroll") for (int n = 0; n < 2; ++n) _Pragma("unroll") for (int k = 0; k < 2; ++k) dst[n][k] = *(const PG8_LAS bf16x8*)(lds + PG8_SB(b, h) + boff + n * 2048 + k * 1024); } while (0)
; #define PG8_MMA(ai, bj, At, Bt) do { __builtin_amdgcn_s_setprio(1); _Pragma("unroll") for (int m = 0; m < 4; ++m) _Pragma("unroll") for (int n = 0; n < 2; ++n) _Pragma("unroll") for (int k = 0; k < 2; ++k) \
;         acc[ai][bj][m][n] = __builtin_amdgcn_mfma_f32_16x16x32_bf16(Bt[n][k], At[m][k], acc[ai][bj][m][n], 0, 0, 0); __builtin_amdgcn_s_setprio(0); } while (0)
; #define PG8_WAIT_V(n) asm volatile("s_waitcnt vmcnt(" #n ")" ::: "memory")
; #define PG8_WAIT_L(n) asm volatile("s_waitcnt lgkmcnt(" #n ")" ::: "memory")
; #define PG8_BAR __builtin_amdgcn_s_barrier()
; #define PG8_SCHED __builtin_amdgcn_sched_barrier(0)
; template <class Epi, class Sched, bool ALIGN_EPI = false, bool SP2 = false>
; __device__ __forceinline__ void gemm_phase(PG8_LAS unsigned char* lds, const Gemm g, const Sched& S, const Epi& E) {
;     ...
;             PG8_LDB(B0, 0, 0); PG8_LDB(B1, 0, 1); PG8_SCHED; PG8_LDA(At, 0, 0); PG8_STAGE(PG8_SA(1, 1), a1 + hstep, voffA);
;             PG8_WAIT_V(8); PG8_WAIT_L(0); PG8_BAR; PG8_MMA(0, 0, At, B0); PG8_MMA(0, 1, At, B1); PG8_BAR; PG8_SCHED;
;             PG8_LDA(At, 0, 1); PG8_STAGE(PG8_SB(0, 0), b2, voffB); PG8_STAGE(PG8_SB(0, 1), b2 + hstep, voffB); PG8_STAGE(PG8_SA(0, 0), a2, voffA);
.LBB0_826:
	ds_read_b128 v[154:157], v150
	ds_read_b128 v[158:161], v150 offset:1024
	ds_read_b128 v[162:165], v150 offset:2048
	ds_read_b128 v[170:173], v150 offset:3072
	ds_read_b128 v[174:177], v151
	ds_read_b128 v[178:181], v151 offset:1024
	ds_read_b128 v[182:185], v151 offset:2048
	ds_read_b128 v[186:189], v151 offset:3072
	s_add_u32 s22, s0, 0xfffc0080
	s_addc_u32 s23, s1, -1
	s_cmp_eq_u32 s44, 12
	s_cselect_b32 s25, s15, s23
	s_cselect_b32 s24, s40, s22
	s_cselect_b32 s23, s13, s43
	s_cselect_b32 s22, s41, s42
	v_lshl_add_u64 v[144:145], s[0:1], 0, v[136:137]
	s_add_i32 m0, s21, 0xc000
	ds_read_b128 v[190:193], v152
	ds_read_b128 v[194:197], v152 offset:1024
	ds_read_b128 v[204:207], v152 offset:2048
	ds_read_b128 v[208:211], v152 offset:3072
	ds_read_b128 v[212:215], v152 offset:4096
	ds_read_b128 v[216:219], v152 offset:5120
	ds_read_b128 v[220:223], v152 offset:6144
	ds_read_b128 v[224:227], v152 offset:7168
	global_load_lds_dwordx4 v[144:145], off
	v_lshl_add_u64 v[144:145], s[0:1], 0, v[138:139]
	s_add_i32 m0, s21, 0xe000
	s_nop 0
	global_load_lds_dwordx4 v[144:145], off
	s_add_u32 s100, s0, 0xfffc0000
	s_addc_u32 s101, s1, -1
	v_lshl_add_u64 v[144:145], s[100:101], 0, v[136:137]
	s_add_i32 m0, s21, 0x8000
	s_nop 0
	global_load_lds_dwordx4 v[144:145], off
	v_lshl_add_u64 v[144:145], s[100:101], 0, v[138:139]
	s_add_i32 m0, s21, 0xa000
	s_nop 0
	global_load_lds_dwordx4 v[144:145], off
	s_waitcnt vmcnt(8)
	s_waitcnt lgkmcnt(0)
	s_barrier
	s_setprio 1
	s_waitcnt lgkmcnt(0)
	v_mfma_f32_16x16x32_bf16 v[124:127], v[154:157], v[190:193], v[124:127]
	v_mfma_f32_16x16x32_bf16 v[120:123], v[162:165], v[190:193], v[120:123]
	v_mfma_f32_16x16x32_bf16 v[108:111], v[154:157], v[204:207], v[108:111]
	v_mfma_f32_16x16x32_bf16 v[104:107], v[162:165], v[204:207], v[104:107]
	v_mfma_f32_16x16x32_bf16 v[92:95], v[154:157], v[212:215], v[92:95]
	v_mfma_f32_16x16x32_bf16 v[88:91], v[162:165], v[212:215], v[88:91]
	v_mfma_f32_16x16x32_bf16 v[76:79], v[154:157], v[220:223], v[76:79]
	v_mfma_f32_16x16x32_bf16 v[72:75], v[162:165], v[220:223], v[72:75]
	v_mfma_f32_16x16x32_bf16 v[124:127], v[158:161], v[194:197], v[124:127]
	v_mfma_f32_16x16x32_bf16 v[120:123], v[170:173], v[194:197], v[120:123]
	v_mfma_f32_16x16x32_bf16 v[108:111], v[158:161], v[208:211], v[108:111]
	v_mfma_f32_16x16x32_bf16 v[104:107], v[170:173], v[208:211], v[104:107]
	v_mfma_f32_16x16x32_bf16 v[92:95], v[158:161], v[216:219], v[92:95]
	v_mfma_f32_16x16x32_bf16 v[88:91], v[170:173], v[216:219], v[88:91]
	v_mfma_f32_16x16x32_bf16 v[76:79], v[158:161], v[224:227], v[76:79]
	v_mfma_f32_16x16x32_bf16 v[72:75], v[170:173], v[224:227], v[72:75]
	s_setprio 0
	s_setprio 1
	v_mfma_f32_16x16x32_bf16 v[116:119], v[174:177], v[190:193], v[116:119]
	v_mfma_f32_16x16x32_bf16 v[112:115], v[182:185], v[190:193], v[112:115]
	v_mfma_f32_16x16x32_bf16 v[100:103], v[174:177], v[204:207], v[100:103]
	v_mfma_f32_16x16x32_bf16 v[96:99], v[182:185], v[204:207], v[96:99]
	v_mfma_f32_16x16x32_bf16 v[84:87], v[174:177], v[212:215], v[84:87]
	v_mfma_f32_16x16x32_bf16 v[80:83], v[182:185], v[212:215], v[80:83]
	v_mfma_f32_16x16x32_bf16 v[68:71], v[174:177], v[220:223], v[68:71]
	v_mfma_f32_16x16x32_bf16 v[64:67], v[182:185], v[220:223], v[64:67]
	v_mfma_f32_16x16x32_bf16 v[116:119], v[178:181], v[194:197], v[116:119]
	v_mfma_f32_16x16x32_bf16 v[112:115], v[186:189], v[194:197], v[112:115]
	v_mfma_f32_16x16x32_bf16 v[100:103], v[178:181], v[208:211], v[100:103]
	v_mfma_f32_16x16x32_bf16 v[96:99], v[186:189], v[208:211], v[96:99]
	v_mfma_f32_16x16x32_bf16 v[84:87], v[178:181], v[216:219], v[84:87]
	v_mfma_f32_16x16x32_bf16 v[80:83], v[186:189], v[216:219], v[80:83]
	v_mfma_f32_16x16x32_bf16 v[68:71], v[178:181], v[224:227], v[68:71]
	v_mfma_f32_16x16x32_bf16 v[64:67], v[186:189], v[224:227], v[64:67]
	s_setprio 0
	s_barrier
	s_add_i32 s45, s46, s26
	v_lshl_add_u64 v[144:145], s[22:23], 0, v[132:133]
	s_mov_b32 m0, s45
	ds_read_b128 v[190:193], v152 offset:16384
	ds_read_b128 v[194:197], v152 offset:17408
	ds_read_b128 v[204:207], v152 offset:18432
	ds_read_b128 v[208:211], v152 offset:19456
	ds_read_b128 v[212:215], v152 offset:20480
	ds_read_b128 v[216:219], v152 offset:21504
	ds_read_b128 v[220:223], v152 offset:22528
	ds_read_b128 v[224:227], v152 offset:23552
	global_load_lds_dwordx4 v[144:145], off
	s_add_i32 m0, s45, 0x2000
	s_add_u32 s48, s22, 0x40000
	v_lshl_add_u64 v[166:167], s[22:23], 0, v[128:129]
	s_addc_u32 s49, s23, 0
	s_add_i32 s45, s38, s26
	global_load_lds_dwordx4 v[166:167], off
	v_lshl_add_u64 v[228:229], s[48:49], 0, v[132:133]
	s_mov_b32 m0, s45
	v_lshl_add_u64 v[230:231], s[24:25], 0, v[130:131]
	global_load_lds_dwordx4 v[228:229], off
	v_lshl_add_u64 v[228:229], s[48:49], 0, v[128:129]
	s_add_i32 m0, s45, 0x2000
	s_nop 0
	global_load_lds_dwordx4 v[228:229], off
	s_waitcnt vmcnt(4)
	s_waitcnt lgkmcnt(0)
	s_barrier
; #define PG8_STAGE(bufoff, gbase, voff) do { _Pragma("unroll") for (int _i = 0; _i < 2; ++_i) \
;         __builtin_amdgcn_global_load_lds((const unsigned*)((const char*)(gbase) + (voff)[_i]), (PG8_LAS unsigned*)(lds + (bufoff) + ldsw + _i * 8192), 16, 0, 0); } while (0)
; #define PG8_LDA(dst, b, h) do { _Pragma("unroll") for (int m = 0; m < 4; ++m) _Pragma("unroll") for (int k = 0; k < 2; ++k) dst[m][k] = *(const PG8_LAS bf16x8*)(lds + PG8_SA(b, h) + aoff + m * 2048 + k * 1024); } while (0)
; #define PG8_LDB(dst, b, h) do { _Pragma("unroll") for (int n = 0; n < 2; ++n) _Pragma("unroll") for (int k = 0; k < 2; ++k) dst[n][k] = *(const PG8_LAS bf16x8*)(lds + PG8_SB(b, h) + boff + n * 2048 + k * 1024); } while (0)
; #define PG8_MMA(ai, bj, At, Bt) do { __builtin_amdgcn_s_setprio(1); _Pragma("unroll") for (int m = 0; m < 4; ++m) _Pragma("unroll") for (int n = 0; n < 2; ++n) _Pragma("unroll") for (int k = 0; k < 2; ++k) \
;         acc[ai][bj][m][n] = __builtin_amdgcn_mfma_f32_16x16x32_bf16(Bt[n][k], At[m][k], acc[ai][bj][m][n], 0, 0, 0); __builtin_amdgcn_s_setprio(0); } while (0)
; #define PG8_WAIT_V(n) asm volatile("s_waitcnt vmcnt(" #n ")" ::: "memory")
; #define PG8_WAIT_L(n) asm volatile("s_waitcnt lgkmcnt(" #n ")" ::: "memory")
; #define PG8_BAR __builtin_amdgcn_s_barrier()
; #define PG8_SCHED __builtin_amdgcn_sched_barrier(0)
; template <class Epi, class Sched, bool ALIGN_EPI = false, bool SP2 = false>
; __device__ __forceinline__ void gemm_phase(PG8_LAS unsigned char* lds, const Gemm g, const Sched& S, const Epi& E) {
;     ...
;             PG8_WAIT_V(8); PG8_WAIT_L(0); PG8_BAR; PG8_MMA(1, 0, At, B0); PG8_MMA(1, 1, At, B1); PG8_BAR; PG8_SCHED;
;             PG8_LDB(B0, 1, 0); PG8_LDB(B1, 1, 1); PG8_SCHED; PG8_LDA(At, 1, 0); PG8_STAGE(PG8_SA(0, 1), a2 + hstep, voffA);
;             PG8_WAIT_V(8); PG8_WAIT_L(0); PG8_BAR; PG8_MMA(0, 0, At, B0); PG8_MMA(0, 1, At, B1); PG8_BAR; PG8_SCHED;
	s_setprio 1
	s_waitcnt lgkmcnt(0)
	v_mfma_f32_16x16x32_bf16 v[60:63], v[154:157], v[190:193], v[60:63]
	v_mfma_f32_16x16x32_bf16 v[56:59], v[162:165], v[190:193], v[56:59]
	v_mfma_f32_16x16x32_bf16 v[44:47], v[154:157], v[204:207], v[44:47]
	v_mfma_f32_16x16x32_bf16 v[40:43], v[162:165], v[204:207], v[40:43]
	v_mfma_f32_16x16x32_bf16 v[28:31], v[154:157], v[212:215], v[28:31]
	v_mfma_f32_16x16x32_bf16 v[24:27], v[162:165], v[212:215], v[24:27]
	v_mfma_f32_16x16x32_bf16 v[12:15], v[154:157], v[220:223], v[12:15]
	v_mfma_f32_16x16x32_bf16 v[8:11], v[162:165], v[220:223], v[8:11]
	v_mfma_f32_16x16x32_bf16 v[60:63], v[158:161], v[194:197], v[60:63]
	v_mfma_f32_16x16x32_bf16 v[56:59], v[170:173], v[194:197], v[56:59]
	v_mfma_f32_16x16x32_bf16 v[44:47], v[158:161], v[208:211], v[44:47]
	v_mfma_f32_16x16x32_bf16 v[40:43], v[170:173], v[208:211], v[40:43]
	v_mfma_f32_16x16x32_bf16 v[28:31], v[158:161], v[216:219], v[28:31]
	v_mfma_f32_16x16x32_bf16 v[24:27], v[170:173], v[216:219], v[24:27]
	v_mfma_f32_16x16x32_bf16 v[12:15], v[158:161], v[224:227], v[12:15]
	v_mfma_f32_16x16x32_bf16 v[8:11], v[170:173], v[224:227], v[8:11]
	s_setprio 0
	s_setprio 1
	v_mfma_f32_16x16x32_bf16 v[52:55], v[174:177], v[190:193], v[52:55]
	v_mfma_f32_16x16x32_bf16 v[48:51], v[182:185], v[190:193], v[48:51]
	v_mfma_f32_16x16x32_bf16 v[36:39], v[174:177], v[204:207], v[36:39]
	v_mfma_f32_16x16x32_bf16 v[32:35], v[182:185], v[204:207], v[32:35]
	v_mfma_f32_16x16x32_bf16 v[20:23], v[174:177], v[212:215], v[20:23]
	v_mfma_f32_16x16x32_bf16 v[16:19], v[182:185], v[212:215], v[16:19]
	v_mfma_f32_16x16x32_bf16 v[4:7], v[174:177], v[220:223], v[4:7]
	v_mfma_f32_16x16x32_bf16 v[0:3], v[182:185], v[220:223], v[0:3]
	v_mfma_f32_16x16x32_bf16 v[52:55], v[178:181], v[194:197], v[52:55]
	v_mfma_f32_16x16x32_bf16 v[48:51], v[186:189], v[194:197], v[48:51]
	v_mfma_f32_16x16x32_bf16 v[36:39], v[178:181], v[208:211], v[36:39]
	v_mfma_f32_16x16x32_bf16 v[32:35], v[186:189], v[208:211], v[32:35]
	v_mfma_f32_16x16x32_bf16 v[20:23], v[178:181], v[216:219], v[20:23]
	v_mfma_f32_16x16x32_bf16 v[16:19], v[186:189], v[216:219], v[16:19]
	v_mfma_f32_16x16x32_bf16 v[4:7], v[178:181], v[224:227], v[4:7]
	v_mfma_f32_16x16x32_bf16 v[0:3], v[186:189], v[224:227], v[0:3]
	s_setprio 0
	s_barrier
	s_add_i32 s45, 0, 0x18000
	v_add_u32_e32 v153, s45, v147
	s_add_i32 s47, 0, 0x1c000
	ds_read_b128 v[154:157], v153
	ds_read_b128 v[158:161], v153 offset:1024
	ds_read_b128 v[162:165], v153 offset:2048
	ds_read_b128 v[170:173], v153 offset:3072
	v_add_u32_e32 v153, s47, v147
	ds_read_b128 v[174:177], v153
	ds_read_b128 v[178:181], v153 offset:1024
	ds_read_b128 v[182:185], v153 offset:2048
	ds_read_b128 v[186:189], v153 offset:3072
	s_add_u32 s24, s24, 0x40000
	s_addc_u32 s25, s25, 0
	s_mov_b32 m0, s30
	v_lshl_add_u64 v[232:233], s[24:25], 0, v[134:135]
	ds_read_b128 v[190:193], v152 offset:32768
	ds_read_b128 v[194:197], v152 offset:33792
	ds_read_b128 v[204:207], v152 offset:34816
	ds_read_b128 v[208:211], v152 offset:35840
	ds_read_b128 v[212:215], v152 offset:36864
	ds_read_b128 v[216:219], v152 offset:37888
	ds_read_b128 v[220:223], v152 offset:38912
	ds_read_b128 v[224:227], v152 offset:39936
	global_load_lds_dwordx4 v[232:233], off
	v_lshl_add_u64 v[232:233], s[24:25], 0, v[130:131]
	s_mov_b32 m0, s31
	s_nop 0
	global_load_lds_dwordx4 v[232:233], off
	s_add_u32 s100, s24, 0xfffc0000
	s_addc_u32 s101, s25, -1
	v_lshl_add_u64 v[232:233], s[100:101], 0, v[134:135]
	s_add_i32 m0, s30, 0xffffc000
	s_nop 0
	global_load_lds_dwordx4 v[232:233], off
	v_lshl_add_u64 v[232:233], s[100:101], 0, v[130:131]
	s_add_i32 m0, s31, 0xffffc000
	s_nop 0
	global_load_lds_dwordx4 v[232:233], off
	s_waitcnt vmcnt(8)
	s_waitcnt lgkmcnt(0)
	s_barrier
; #define PG8_STAGE(bufoff, gbase, voff) do { _Pragma("unroll") for (int _i = 0; _i < 2; ++_i) \
;         __builtin_amdgcn_global_load_lds((const unsigned*)((const char*)(gbase) + (voff)[_i]), (PG8_LAS unsigned*)(lds + (bufoff) + ldsw + _i * 8192), 16, 0, 0); } while (0)
; #define PG8_LDA(dst, b, h) do { _Pragma("unroll") for (int m = 0; m < 4; ++m) _Pragma("unroll") for (int k = 0; k < 2; ++k) dst[m][k] = *(const PG8_LAS bf16x8*)(lds + PG8_SA(b, h) + aoff + m * 2048 + k * 1024); } while (0)
; #define PG8_MMA(ai, bj, At, Bt) do { __builtin_amdgcn_s_setprio(1); _Pragma("unroll") for (int m = 0; m < 4; ++m) _Pragma("unroll") for (int n = 0; n < 2; ++n) _Pragma("unroll") for (int k = 0; k < 2; ++k) \
;         acc[ai][bj][m][n] = __builtin_amdgcn_mfma_f32_16x16x32_bf16(Bt[n][k], At[m][k], acc[ai][bj][m][n], 0, 0, 0); __builtin_amdgcn_s_setprio(0); } while (0)
; #define PG8_WAIT_V(n) asm volatile("s_waitcnt vmcnt(" #n ")" ::: "memory")
; #define PG8_WAIT_L(n) asm volatile("s_waitcnt lgkmcnt(" #n ")" ::: "memory")
; #define PG8_BAR __builtin_amdgcn_s_barrier()
; #define PG8_SCHED __builtin_amdgcn_sched_barrier(0)
; template <class Epi, class Sched, bool ALIGN_EPI = false, bool SP2 = false>
; __device__ __forceinline__ void gemm_phase(PG8_LAS unsigned char* lds, const Gemm g, const Sched& S, const Epi& E) {
;     ...
;             PG8_WAIT_V(8); PG8_WAIT_L(0); PG8_BAR; PG8_MMA(0, 0, At, B0); PG8_MMA(0, 1, At, B1); PG8_BAR; PG8_SCHED;
;             PG8_LDA(At, 1, 1); PG8_STAGE(PG8_SB(1, 0), b3, voffB); PG8_STAGE(PG8_SB(1, 1), b3 + hstep, voffB); PG8_STAGE(PG8_SA(1, 0), a3, voffA);
;             PG8_WAIT_V(8); PG8_WAIT_L(0); PG8_BAR; PG8_MMA(1, 0, At, B0); PG8_MMA(1, 1, At, B1); PG8_BAR; PG8_SCHED;
	s_setprio 1
	s_waitcnt lgkmcnt(0)
	v_mfma_f32_16x16x32_bf16 v[124:127], v[154:157], v[190:193], v[124:127]
	v_mfma_f32_16x16x32_bf16 v[120:123], v[162:165], v[190:193], v[120:123]
	v_mfma_f32_16x16x32_bf16 v[108:111], v[154:157], v[204:207], v[108:111]
	v_mfma_f32_16x16x32_bf16 v[104:107], v[162:165], v[204:207], v[104:107]
	v_mfma_f32_16x16x32_bf16 v[92:95], v[154:157], v[212:215], v[92:95]
	v_mfma_f32_16x16x32_bf16 v[88:91], v[162:165], v[212:215], v[88:91]
	v_mfma_f32_16x16x32_bf16 v[76:79], v[154:157], v[220:223], v[76:79]
	v_mfma_f32_16x16x32_bf16 v[72:75], v[162:165], v[220:223], v[72:75]
	v_mfma_f32_16x16x32_bf16 v[124:127], v[158:161], v[194:197], v[124:127]
	v_mfma_f32_16x16x32_bf16 v[120:123], v[170:173], v[194:197], v[120:123]
	v_mfma_f32_16x16x32_bf16 v[108:111], v[158:161], v[208:211], v[108:111]
	v_mfma_f32_16x16x32_bf16 v[104:107], v[170:173], v[208:211], v[104:107]
	v_mfma_f32_16x16x32_bf16 v[92:95], v[158:161], v[216:219], v[92:95]
	v_mfma_f32_16x16x32_bf16 v[88:91], v[170:173], v[216:219], v[88:91]
	v_mfma_f32_16x16x32_bf16 v[76:79], v[158:161], v[224:227], v[76:79]
	v_mfma_f32_16x16x32_bf16 v[72:75], v[170:173], v[224:227], v[72:75]
	s_setprio 0
	s_setprio 1
	v_mfma_f32_16x16x32_bf16 v[116:119], v[174:177], v[190:193], v[116:119]
	v_mfma_f32_16x16x32_bf16 v[112:115], v[182:185], v[190:193], v[112:115]
	v_mfma_f32_16x16x32_bf16 v[100:103], v[174:177], v[204:207], v[100:103]
	v_mfma_f32_16x16x32_bf16 v[96:99], v[182:185], v[204:207], v[96:99]
	v_mfma_f32_16x16x32_bf16 v[84:87], v[174:177], v[212:215], v[84:87]
	v_mfma_f32_16x16x32_bf16 v[80:83], v[182:185], v[212:215], v[80:83]
	v_mfma_f32_16x16x32_bf16 v[68:71], v[174:177], v[220:223], v[68:71]
	v_mfma_f32_16x16x32_bf16 v[64:67], v[182:185], v[220:223], v[64:67]
	v_mfma_f32_16x16x32_bf16 v[116:119], v[178:181], v[194:197], v[116:119]
	v_mfma_f32_16x16x32_bf16 v[112:115], v[186:189], v[194:197], v[112:115]
	v_mfma_f32_16x16x32_bf16 v[100:103], v[178:181], v[208:211], v[100:103]
	v_mfma_f32_16x16x32_bf16 v[96:99], v[186:189], v[208:211], v[96:99]
	v_mfma_f32_16x16x32_bf16 v[84:87], v[178:181], v[216:219], v[84:87]
	v_mfma_f32_16x16x32_bf16 v[80:83], v[186:189], v[216:219], v[80:83]
	v_mfma_f32_16x16x32_bf16 v[68:71], v[178:181], v[224:227], v[68:71]
	v_mfma_f32_16x16x32_bf16 v[64:67], v[186:189], v[224:227], v[64:67]
	s_setprio 0
	s_barrier
	s_add_i32 s24, s45, s26
	v_lshl_add_u64 v[144:145], v[144:145], 0, s[8:9]
	s_mov_b32 m0, s24
	ds_read_b128 v[190:193], v152 offset:49152
	ds_read_b128 v[194:197], v152 offset:50176
	ds_read_b128 v[204:207], v152 offset:51200
	ds_read_b128 v[208:211], v152 offset:52224
	ds_read_b128 v[212:215], v152 offset:53248
	ds_read_b128 v[216:219], v152 offset:54272
	ds_read_b128 v[220:223], v152 offset:55296
	ds_read_b128 v[224:227], v152 offset:56320
	global_load_lds_dwordx4 v[144:145], off
	s_add_i32 m0, s24, 0x2000
	s_add_u32 s22, s22, 0x40080
	v_lshl_add_u64 v[144:145], v[166:167], 0, s[8:9]
	s_addc_u32 s23, s23, 0
	s_add_i32 s24, s47, s26
	global_load_lds_dwordx4 v[144:145], off
	v_lshl_add_u64 v[144:145], s[22:23], 0, v[132:133]
	s_mov_b32 m0, s24
	s_nop 0
	global_load_lds_dwordx4 v[144:145], off
	v_lshl_add_u64 v[144:145], s[22:23], 0, v[128:129]
	s_add_i32 m0, s24, 0x2000
	s_nop 0
	global_load_lds_dwordx4 v[144:145], off
	s_waitcnt vmcnt(4)
	s_waitcnt lgkmcnt(0)
	s_barrier
	s_setprio 1
	s_waitcnt lgkmcnt(0)
	v_mfma_f32_16x16x32_bf16 v[60:63], v[154:157], v[190:193], v[60:63]
	v_mfma_f32_16x16x32_bf16 v[56:59], v[162:165], v[190:193], v[56:59]
	v_mfma_f32_16x16x32_bf16 v[44:47], v[154:157], v[204:207], v[44:47]
	v_mfma_f32_16x16x32_bf16 v[40:43], v[162:165], v[204:207], v[40:43]
	v_mfma_f32_16x16x32_bf16 v[28:31], v[154:157], v[212:215], v[28:31]
	v_mfma_f32_16x16x32_bf16 v[24:27], v[162:165], v[212:215], v[24:27]
	v_mfma_f32_16x16x32_bf16 v[12:15], v[154:157], v[220:223], v[12:15]
	v_mfma_f32_16x16x32_bf16 v[8:11], v[162:165], v[220:223], v[8:11]
	v_mfma_f32_16x16x32_bf16 v[60:63], v[158:161], v[194:197], v[60:63]
	v_mfma_f32_16x16x32_bf16 v[56:59], v[170:173], v[194:197], v[56:59]
	v_mfma_f32_16x16x32_bf16 v[44:47], v[158:161], v[208:211], v[44:47]
	v_mfma_f32_16x16x32_bf16 v[40:43], v[170:173], v[208:211], v[40:43]
	v_mfma_f32_16x16x32_bf16 v[28:31], v[158:161], v[216:219], v[28:31]
	v_mfma_f32_16x16x32_bf16 v[24:27], v[170:173], v[216:219], v[24:27]
	v_mfma_f32_16x16x32_bf16 v[12:15], v[158:161], v[224:227], v[12:15]
	v_mfma_f32_16x16x32_bf16 v[8:11], v[170:173], v[224:227], v[8:11]
	s_setprio 0
	s_setprio 1
	v_mfma_f32_16x16x32_bf16 v[52:55], v[174:177], v[190:193], v[52:55]
	v_mfma_f32_16x16x32_bf16 v[48:51], v[182:185], v[190:193], v[48:51]
	v_mfma_f32_16x16x32_bf16 v[36:39], v[174:177], v[204:207], v[36:39]
	v_mfma_f32_16x16x32_bf16 v[32:35], v[182:185], v[204:207], v[32:35]
	v_mfma_f32_16x16x32_bf16 v[20:23], v[174:177], v[212:215], v[20:23]
	v_mfma_f32_16x16x32_bf16 v[16:19], v[182:185], v[212:215], v[16:19]
	v_mfma_f32_16x16x32_bf16 v[4:7], v[174:177], v[220:223], v[4:7]
	v_mfma_f32_16x16x32_bf16 v[0:3], v[182:185], v[220:223], v[0:3]
	v_mfma_f32_16x16x32_bf16 v[52:55], v[178:181], v[194:197], v[52:55]
	v_mfma_f32_16x16x32_bf16 v[48:51], v[186:189], v[194:197], v[48:51]
	v_mfma_f32_16x16x32_bf16 v[36:39], v[178:181], v[208:211], v[36:39]
	v_mfma_f32_16x16x32_bf16 v[32:35], v[186:189], v[208:211], v[32:35]
	v_mfma_f32_16x16x32_bf16 v[20:23], v[178:181], v[216:219], v[20:23]
	v_mfma_f32_16x16x32_bf16 v[16:19], v[186:189], v[216:219], v[16:19]
	v_mfma_f32_16x16x32_bf16 v[4:7], v[178:181], v[224:227], v[4:7]
	v_mfma_f32_16x16x32_bf16 v[0:3], v[186:189], v[224:227], v[0:3]
	s_setprio 0
	s_barrier
	s_add_i32 s44, s44, 2
	s_add_u32 s0, s0, 0x100
	s_addc_u32 s1, s1, 0
	s_add_u32 s42, s42, 0x100
	s_addc_u32 s43, s43, 0
	s_cmp_gt_u32 s44, 13
	s_cbranch_scc0 .LBB0_826
	s_and_b64 vcc, exec, s[10:11]
	s_cbranch_vccz .LBB0_829
	s_barrier

; #define PG8_STAGE(bufoff, gbase, voff) do { _Pragma("unroll") for (int _i = 0; _i < 2; ++_i) \
;         __builtin_amdgcn_global_load_lds((const unsigned*)((const char*)(gbase) + (voff)[_i]), (PG8_LAS unsigned*)(lds + (bufoff) + ldsw + _i * 8192), 16, 0, 0); } while (0)
; #define PG8_LDA(dst, b, h) do { _Pragma("unroll") for (int m = 0; m < 4; ++m) _Pragma("unroll") for (int k = 0; k < 2; ++k) dst[m][k] = *(const PG8_LAS bf16x8*)(lds + PG8_SA(b, h) + aoff + m * 2048 + k * 1024); } while (0)
; #define PG8_LDB(dst, b, h) do { _Pragma("unroll") for (int n = 0; n < 2; ++n) _Pragma("unroll") for (int k = 0; k < 2; ++k) dst[n][k] = *(const PG8_LAS bf16x8*)(lds + PG8_SB(b, h) + boff + n * 2048 + k * 1024); } while (0)
; #define PG8_MMA(ai, bj, At, Bt) do { __builtin_amdgcn_s_setprio(1); _Pragma("unroll") for (int m = 0; m < 4; ++m) _Pragma("unroll") for (int n = 0; n < 2; ++n) _Pragma("unroll") for (int k = 0; k < 2; ++k) \
;         acc[ai][bj][m][n] = __builtin_amdgcn_mfma_f32_16x16x32_bf16(Bt[n][k], At[m][k], acc[ai][bj][m][n], 0, 0, 0); __builtin_amdgcn_s_setprio(0); } while (0)
; #define PG8_WAIT_V(n) asm volatile("s_waitcnt vmcnt(" #n ")" ::: "memory")
; #define PG8_WAIT_L(n) asm volatile("s_waitcnt lgkmcnt(" #n ")" ::: "memory")
; #define PG8_BAR __builtin_amdgcn_s_barrier()
; #define PG8_SCHED __builtin_amdgcn_sched_barrier(0)
; template <class Epi, class Sched, bool ALIGN_EPI = false, bool SP2 = false>
; __device__ __forceinline__ void gemm_phase(PG8_LAS unsigned char* lds, const Gemm g, const Sched& S, const Epi& E) {
;     ...
;             PG8_LDB(B0, 0, 0); PG8_LDB(B1, 0, 1); PG8_SCHED; PG8_LDA(At, 0, 0); PG8_STAGE(PG8_SA(1, 1), a1 + hstep, voffA);
;             PG8_WAIT_V(8); PG8_WAIT_L(0); PG8_BAR; PG8_MMA(0, 0, At, B0); PG8_MMA(0, 1, At, B1); PG8_BAR; PG8_SCHED;
;             PG8_LDA(At, 0, 1); PG8_STAGE(PG8_SB(0, 0), b2, voffB); PG8_STAGE(PG8_SB(0, 1), b2 + hstep, voffB); PG8_STAGE(PG8_SA(0, 0), a2, voffA);
.LBB0_908:
	ds_read_b128 v[128:131], v189
	ds_read_b128 v[132:135], v189 offset:1024
	ds_read_b128 v[136:139], v189 offset:2048
	ds_read_b128 v[140:143], v189 offset:3072
	ds_read_b128 v[144:147], v190
	ds_read_b128 v[148:151], v190 offset:1024
	ds_read_b128 v[152:155], v190 offset:2048
	ds_read_b128 v[156:159], v190 offset:3072
	s_add_u32 s24, s22, 0x100
	s_addc_u32 s25, s23, 0
	s_cmp_eq_u32 s65, 40
	s_cselect_b32 s29, s9, s25
	s_cselect_b32 s28, s8, s24
	s_cselect_b32 s27, s21, s63
	s_cselect_b32 s26, s20, s62
	v_lshl_add_u64 v[182:183], s[22:23], 0, v[170:171]
	s_add_i32 m0, s31, 0xc000
	ds_read_b128 v[178:181], v191
	ds_read_b128 v[196:199], v191 offset:1024
	ds_read_b128 v[204:207], v191 offset:2048
	ds_read_b128 v[208:211], v191 offset:3072
	ds_read_b128 v[212:215], v191 offset:4096
	ds_read_b128 v[216:219], v191 offset:5120
	ds_read_b128 v[220:223], v191 offset:6144
	ds_read_b128 v[224:227], v191 offset:7168
	global_load_lds_dwordx4 v[182:183], off
	v_lshl_add_u64 v[182:183], s[22:23], 0, v[172:173]
	s_add_i32 m0, s31, 0xe000
	s_nop 0
	global_load_lds_dwordx4 v[182:183], off
	s_add_u32 s100, s22, 0xfff50000
	s_addc_u32 s101, s23, -1
	v_lshl_add_u64 v[182:183], s[100:101], 0, v[170:171]
	s_add_i32 m0, s31, 0x8000
	s_nop 0
	global_load_lds_dwordx4 v[182:183], off
	v_lshl_add_u64 v[182:183], s[100:101], 0, v[172:173]
	s_add_i32 m0, s31, 0xa000
	s_nop 0
	global_load_lds_dwordx4 v[182:183], off
	s_waitcnt vmcnt(8)
	s_waitcnt lgkmcnt(0)
	s_barrier
	s_setprio 1
	s_waitcnt lgkmcnt(0)
	v_mfma_f32_16x16x32_bf16 v[124:127], v[128:131], v[178:181], v[124:127]
	v_mfma_f32_16x16x32_bf16 v[120:123], v[136:139], v[178:181], v[120:123]
	v_mfma_f32_16x16x32_bf16 v[108:111], v[128:131], v[204:207], v[108:111]
	v_mfma_f32_16x16x32_bf16 v[104:107], v[136:139], v[204:207], v[104:107]
	v_mfma_f32_16x16x32_bf16 v[92:95], v[128:131], v[212:215], v[92:95]
	v_mfma_f32_16x16x32_bf16 v[88:91], v[136:139], v[212:215], v[88:91]
	v_mfma_f32_16x16x32_bf16 v[76:79], v[128:131], v[220:223], v[76:79]
	v_mfma_f32_16x16x32_bf16 v[72:75], v[136:139], v[220:223], v[72:75]
	v_mfma_f32_16x16x32_bf16 v[124:127], v[132:135], v[196:199], v[124:127]
	v_mfma_f32_16x16x32_bf16 v[120:123], v[140:143], v[196:199], v[120:123]
	v_mfma_f32_16x16x32_bf16 v[108:111], v[132:135], v[208:211], v[108:111]
	v_mfma_f32_16x16x32_bf16 v[104:107], v[140:143], v[208:211], v[104:107]
	v_mfma_f32_16x16x32_bf16 v[92:95], v[132:135], v[216:219], v[92:95]
	v_mfma_f32_16x16x32_bf16 v[88:91], v[140:143], v[216:219], v[88:91]
	v_mfma_f32_16x16x32_bf16 v[76:79], v[132:135], v[224:227], v[76:79]
	v_mfma_f32_16x16x32_bf16 v[72:75], v[140:143], v[224:227], v[72:75]
	s_setprio 0
	s_setprio 1
	v_mfma_f32_16x16x32_bf16 v[116:119], v[144:147], v[178:181], v[116:119]
	v_mfma_f32_16x16x32_bf16 v[112:115], v[152:155], v[178:181], v[112:115]
	v_mfma_f32_16x16x32_bf16 v[100:103], v[144:147], v[204:207], v[100:103]
	v_mfma_f32_16x16x32_bf16 v[96:99], v[152:155], v[204:207], v[96:99]
	v_mfma_f32_16x16x32_bf16 v[84:87], v[144:147], v[212:215], v[84:87]
	v_mfma_f32_16x16x32_bf16 v[80:83], v[152:155], v[212:215], v[80:83]
	v_mfma_f32_16x16x32_bf16 v[68:71], v[144:147], v[220:223], v[68:71]
	v_mfma_f32_16x16x32_bf16 v[64:67], v[152:155], v[220:223], v[64:67]
	v_mfma_f32_16x16x32_bf16 v[116:119], v[148:151], v[196:199], v[116:119]
	v_mfma_f32_16x16x32_bf16 v[112:115], v[156:159], v[196:199], v[112:115]
	v_mfma_f32_16x16x32_bf16 v[100:103], v[148:151], v[208:211], v[100:103]
	v_mfma_f32_16x16x32_bf16 v[96:99], v[156:159], v[208:211], v[96:99]
	v_mfma_f32_16x16x32_bf16 v[84:87], v[148:151], v[216:219], v[84:87]
	v_mfma_f32_16x16x32_bf16 v[80:83], v[156:159], v[216:219], v[80:83]
	v_mfma_f32_16x16x32_bf16 v[68:71], v[148:151], v[224:227], v[68:71]
	v_mfma_f32_16x16x32_bf16 v[64:67], v[156:159], v[224:227], v[64:67]
	s_setprio 0
	s_barrier
	s_add_i32 s22, s46, s30
	v_lshl_add_u64 v[182:183], s[26:27], 0, v[162:163]
	s_mov_b32 m0, s22
	ds_read_b128 v[178:181], v191 offset:16384
	ds_read_b128 v[196:199], v191 offset:17408
	ds_read_b128 v[204:207], v191 offset:18432
	ds_read_b128 v[208:211], v191 offset:19456
	ds_read_b128 v[212:215], v191 offset:20480
	ds_read_b128 v[216:219], v191 offset:21504
	ds_read_b128 v[220:223], v191 offset:22528
	ds_read_b128 v[224:227], v191 offset:23552
	global_load_lds_dwordx4 v[182:183], off
	s_add_i32 m0, s22, 0x2000
	s_add_u32 s22, s26, 0xb0000
	v_lshl_add_u64 v[200:201], s[26:27], 0, v[166:167]
	s_addc_u32 s23, s27, 0
	s_add_i32 s66, s47, s30
	global_load_lds_dwordx4 v[200:201], off
	v_lshl_add_u64 v[228:229], s[22:23], 0, v[162:163]
	s_mov_b32 m0, s66
	v_lshl_add_u64 v[230:231], s[28:29], 0, v[164:165]
	global_load_lds_dwordx4 v[228:229], off
	v_lshl_add_u64 v[228:229], s[22:23], 0, v[166:167]
	s_add_i32 m0, s66, 0x2000
	s_nop 0
	global_load_lds_dwordx4 v[228:229], off
	s_waitcnt vmcnt(4)
	s_waitcnt lgkmcnt(0)
	s_barrier
; #define PG8_STAGE(bufoff, gbase, voff) do { _Pragma("unroll") for (int _i = 0; _i < 2; ++_i) \
;         __builtin_amdgcn_global_load_lds((const unsigned*)((const char*)(gbase) + (voff)[_i]), (PG8_LAS unsigned*)(lds + (bufoff) + ldsw + _i * 8192), 16, 0, 0); } while (0)
; #define PG8_LDA(dst, b, h) do { _Pragma("unroll") for (int m = 0; m < 4; ++m) _Pragma("unroll") for (int k = 0; k < 2; ++k) dst[m][k] = *(const PG8_LAS bf16x8*)(lds + PG8_SA(b, h) + aoff + m * 2048 + k * 1024); } while (0)
; #define PG8_LDB(dst, b, h) do { _Pragma("unroll") for (int n = 0; n < 2; ++n) _Pragma("unroll") for (int k = 0; k < 2; ++k) dst[n][k] = *(const PG8_LAS bf16x8*)(lds + PG8_SB(b, h) + boff + n * 2048 + k * 1024); } while (0)
; #define PG8_MMA(ai, bj, At, Bt) do { __builtin_amdgcn_s_setprio(1); _Pragma("unroll") for (int m = 0; m < 4; ++m) _Pragma("unroll") for (int n = 0; n < 2; ++n) _Pragma("unroll") for (int k = 0; k < 2; ++k) \
;         acc[ai][bj][m][n] = __builtin_amdgcn_mfma_f32_16x16x32_bf16(Bt[n][k], At[m][k], acc[ai][bj][m][n], 0, 0, 0); __builtin_amdgcn_s_setprio(0); } while (0)
; #define PG8_WAIT_V(n) asm volatile("s_waitcnt vmcnt(" #n ")" ::: "memory")
; #define PG8_WAIT_L(n) asm volatile("s_waitcnt lgkmcnt(" #n ")" ::: "memory")
; #define PG8_BAR __builtin_amdgcn_s_barrier()
; #define PG8_SCHED __builtin_amdgcn_sched_barrier(0)
; template <class Epi, class Sched, bool ALIGN_EPI = false, bool SP2 = false>
; __device__ __forceinline__ void gemm_phase(PG8_LAS unsigned char* lds, const Gemm g, const Sched& S, const Epi& E) {
;     ...
;             PG8_WAIT_V(8); PG8_WAIT_L(0); PG8_BAR; PG8_MMA(1, 0, At, B0); PG8_MMA(1, 1, At, B1); PG8_BAR; PG8_SCHED;
;             PG8_LDB(B0, 1, 0); PG8_LDB(B1, 1, 1); PG8_SCHED; PG8_LDA(At, 1, 0); PG8_STAGE(PG8_SA(0, 1), a2 + hstep, voffA);
;             PG8_WAIT_V(8); PG8_WAIT_L(0); PG8_BAR; PG8_MMA(0, 0, At, B0); PG8_MMA(0, 1, At, B1); PG8_BAR; PG8_SCHED;
	s_setprio 1
	s_waitcnt lgkmcnt(0)
	v_mfma_f32_16x16x32_bf16 v[60:63], v[128:131], v[178:181], v[60:63]
	v_mfma_f32_16x16x32_bf16 v[56:59], v[136:139], v[178:181], v[56:59]
	v_mfma_f32_16x16x32_bf16 v[44:47], v[128:131], v[204:207], v[44:47]
	v_mfma_f32_16x16x32_bf16 v[40:43], v[136:139], v[204:207], v[40:43]
	v_mfma_f32_16x16x32_bf16 v[28:31], v[128:131], v[212:215], v[28:31]
	v_mfma_f32_16x16x32_bf16 v[24:27], v[136:139], v[212:215], v[24:27]
	v_mfma_f32_16x16x32_bf16 v[12:15], v[128:131], v[220:223], v[12:15]
	v_mfma_f32_16x16x32_bf16 v[8:11], v[136:139], v[220:223], v[8:11]
	v_mfma_f32_16x16x32_bf16 v[60:63], v[132:135], v[196:199], v[60:63]
	v_mfma_f32_16x16x32_bf16 v[56:59], v[140:143], v[196:199], v[56:59]
	v_mfma_f32_16x16x32_bf16 v[44:47], v[132:135], v[208:211], v[44:47]
	v_mfma_f32_16x16x32_bf16 v[40:43], v[140:143], v[208:211], v[40:43]
	v_mfma_f32_16x16x32_bf16 v[28:31], v[132:135], v[216:219], v[28:31]
	v_mfma_f32_16x16x32_bf16 v[24:27], v[140:143], v[216:219], v[24:27]
	v_mfma_f32_16x16x32_bf16 v[12:15], v[132:135], v[224:227], v[12:15]
	v_mfma_f32_16x16x32_bf16 v[8:11], v[140:143], v[224:227], v[8:11]
	s_setprio 0
	s_setprio 1
	v_mfma_f32_16x16x32_bf16 v[52:55], v[144:147], v[178:181], v[52:55]
	v_mfma_f32_16x16x32_bf16 v[48:51], v[152:155], v[178:181], v[48:51]
	v_mfma_f32_16x16x32_bf16 v[36:39], v[144:147], v[204:207], v[36:39]
	v_mfma_f32_16x16x32_bf16 v[32:35], v[152:155], v[204:207], v[32:35]
	v_mfma_f32_16x16x32_bf16 v[20:23], v[144:147], v[212:215], v[20:23]
	v_mfma_f32_16x16x32_bf16 v[16:19], v[152:155], v[212:215], v[16:19]
	v_mfma_f32_16x16x32_bf16 v[4:7], v[144:147], v[220:223], v[4:7]
	v_mfma_f32_16x16x32_bf16 v[0:3], v[152:155], v[220:223], v[0:3]
	v_mfma_f32_16x16x32_bf16 v[52:55], v[148:151], v[196:199], v[52:55]
	v_mfma_f32_16x16x32_bf16 v[48:51], v[156:159], v[196:199], v[48:51]
	v_mfma_f32_16x16x32_bf16 v[36:39], v[148:151], v[208:211], v[36:39]
	v_mfma_f32_16x16x32_bf16 v[32:35], v[156:159], v[208:211], v[32:35]
	v_mfma_f32_16x16x32_bf16 v[20:23], v[148:151], v[216:219], v[20:23]
	v_mfma_f32_16x16x32_bf16 v[16:19], v[156:159], v[216:219], v[16:19]
	v_mfma_f32_16x16x32_bf16 v[4:7], v[148:151], v[224:227], v[4:7]
	v_mfma_f32_16x16x32_bf16 v[0:3], v[156:159], v[224:227], v[0:3]
	s_setprio 0
	s_barrier
	s_add_i32 s66, 0, 0x18000
	s_add_i32 s67, 0, 0x1c000
	v_add_u32_e32 v140, s66, v185
	v_add_u32_e32 v156, s67, v185
	ds_read_b128 v[128:131], v140
	ds_read_b128 v[132:135], v140 offset:1024
	ds_read_b128 v[136:139], v140 offset:2048
	ds_read_b128 v[140:143], v140 offset:3072
	ds_read_b128 v[144:147], v156
	ds_read_b128 v[148:151], v156 offset:1024
	ds_read_b128 v[152:155], v156 offset:2048
	ds_read_b128 v[156:159], v156 offset:3072
	s_add_u32 s22, s28, 0xb0000
	s_addc_u32 s23, s29, 0
	s_mov_b32 m0, s34
	v_lshl_add_u64 v[232:233], s[22:23], 0, v[160:161]
	ds_read_b128 v[178:181], v191 offset:32768
	ds_read_b128 v[196:199], v191 offset:33792
	ds_read_b128 v[204:207], v191 offset:34816
	ds_read_b128 v[208:211], v191 offset:35840
	ds_read_b128 v[212:215], v191 offset:36864
	ds_read_b128 v[216:219], v191 offset:37888
	ds_read_b128 v[220:223], v191 offset:38912
	ds_read_b128 v[224:227], v191 offset:39936
	global_load_lds_dwordx4 v[232:233], off
	v_lshl_add_u64 v[232:233], s[22:23], 0, v[164:165]
	s_mov_b32 m0, s35
	s_nop 0
	global_load_lds_dwordx4 v[232:233], off
	s_add_u32 s100, s22, 0xfff50000
	s_addc_u32 s101, s23, -1
	v_lshl_add_u64 v[232:233], s[100:101], 0, v[160:161]
	s_add_i32 m0, s34, 0xffffc000
	s_nop 0
	global_load_lds_dwordx4 v[232:233], off
	v_lshl_add_u64 v[232:233], s[100:101], 0, v[164:165]
	s_add_i32 m0, s35, 0xffffc000
	s_nop 0
	global_load_lds_dwordx4 v[232:233], off
	s_waitcnt vmcnt(8)
	s_waitcnt lgkmcnt(0)
	s_barrier
; #define PG8_STAGE(bufoff, gbase, voff) do { _Pragma("unroll") for (int _i = 0; _i < 2; ++_i) \
;         __builtin_amdgcn_global_load_lds((const unsigned*)((const char*)(gbase) + (voff)[_i]), (PG8_LAS unsigned*)(lds + (bufoff) + ldsw + _i * 8192), 16, 0, 0); } while (0)
; #define PG8_LDA(dst, b, h) do { _Pragma("unroll") for (int m = 0; m < 4; ++m) _Pragma("unroll") for (int k = 0; k < 2; ++k) dst[m][k] = *(const PG8_LAS bf16x8*)(lds + PG8_SA(b, h) + aoff + m * 2048 + k * 1024); } while (0)
; #define PG8_MMA(ai, bj, At, Bt) do { __builtin_amdgcn_s_setprio(1); _Pragma("unroll") for (int m = 0; m < 4; ++m) _Pragma("unroll") for (int n = 0; n < 2; ++n) _Pragma("unroll") for (int k = 0; k < 2; ++k) \
;         acc[ai][bj][m][n] = __builtin_amdgcn_mfma_f32_16x16x32_bf16(Bt[n][k], At[m][k], acc[ai][bj][m][n], 0, 0, 0); __builtin_amdgcn_s_setprio(0); } while (0)
; #define PG8_WAIT_V(n) asm volatile("s_waitcnt vmcnt(" #n ")" ::: "memory")
; #define PG8_WAIT_L(n) asm volatile("s_waitcnt lgkmcnt(" #n ")" ::: "memory")
; #define PG8_BAR __builtin_amdgcn_s_barrier()
; #define PG8_SCHED __builtin_amdgcn_sched_barrier(0)
; template <class Epi, class Sched, bool ALIGN_EPI = false, bool SP2 = false>
; __device__ __forceinline__ void gemm_phase(PG8_LAS unsigned char* lds, const Gemm g, const Sched& S, const Epi& E) {
;     ...
;             PG8_WAIT_V(8); PG8_WAIT_L(0); PG8_BAR; PG8_MMA(0, 0, At, B0); PG8_MMA(0, 1, At, B1); PG8_BAR; PG8_SCHED;
;             PG8_LDA(At, 1, 1); PG8_STAGE(PG8_SB(1, 0), b3, voffB); PG8_STAGE(PG8_SB(1, 1), b3 + hstep, voffB); PG8_STAGE(PG8_SA(1, 0), a3, voffA);
;             PG8_WAIT_V(8); PG8_WAIT_L(0); PG8_BAR; PG8_MMA(1, 0, At, B0); PG8_MMA(1, 1, At, B1); PG8_BAR; PG8_SCHED;
	s_setprio 1
	s_waitcnt lgkmcnt(0)
	v_mfma_f32_16x16x32_bf16 v[124:127], v[128:131], v[178:181], v[124:127]
	v_mfma_f32_16x16x32_bf16 v[120:123], v[136:139], v[178:181], v[120:123]
	v_mfma_f32_16x16x32_bf16 v[108:111], v[128:131], v[204:207], v[108:111]
	v_mfma_f32_16x16x32_bf16 v[104:107], v[136:139], v[204:207], v[104:107]
	v_mfma_f32_16x16x32_bf16 v[92:95], v[128:131], v[212:215], v[92:95]
	v_mfma_f32_16x16x32_bf16 v[88:91], v[136:139], v[212:215], v[88:91]
	v_mfma_f32_16x16x32_bf16 v[76:79], v[128:131], v[220:223], v[76:79]
	v_mfma_f32_16x16x32_bf16 v[72:75], v[136:139], v[220:223], v[72:75]
	v_mfma_f32_16x16x32_bf16 v[124:127], v[132:135], v[196:199], v[124:127]
	v_mfma_f32_16x16x32_bf16 v[120:123], v[140:143], v[196:199], v[120:123]
	v_mfma_f32_16x16x32_bf16 v[108:111], v[132:135], v[208:211], v[108:111]
	v_mfma_f32_16x16x32_bf16 v[104:107], v[140:143], v[208:211], v[104:107]
	v_mfma_f32_16x16x32_bf16 v[92:95], v[132:135], v[216:219], v[92:95]
	v_mfma_f32_16x16x32_bf16 v[88:91], v[140:143], v[216:219], v[88:91]
	v_mfma_f32_16x16x32_bf16 v[76:79], v[132:135], v[224:227], v[76:79]
	v_mfma_f32_16x16x32_bf16 v[72:75], v[140:143], v[224:227], v[72:75]
	s_setprio 0
	s_setprio 1
	v_mfma_f32_16x16x32_bf16 v[116:119], v[144:147], v[178:181], v[116:119]
	v_mfma_f32_16x16x32_bf16 v[112:115], v[152:155], v[178:181], v[112:115]
	v_mfma_f32_16x16x32_bf16 v[100:103], v[144:147], v[204:207], v[100:103]
	v_mfma_f32_16x16x32_bf16 v[96:99], v[152:155], v[204:207], v[96:99]
	v_mfma_f32_16x16x32_bf16 v[84:87], v[144:147], v[212:215], v[84:87]
	v_mfma_f32_16x16x32_bf16 v[80:83], v[152:155], v[212:215], v[80:83]
	v_mfma_f32_16x16x32_bf16 v[68:71], v[144:147], v[220:223], v[68:71]
	v_mfma_f32_16x16x32_bf16 v[64:67], v[152:155], v[220:223], v[64:67]
	v_mfma_f32_16x16x32_bf16 v[116:119], v[148:151], v[196:199], v[116:119]
	v_mfma_f32_16x16x32_bf16 v[112:115], v[156:159], v[196:199], v[112:115]
	v_mfma_f32_16x16x32_bf16 v[100:103], v[148:151], v[208:211], v[100:103]
	v_mfma_f32_16x16x32_bf16 v[96:99], v[156:159], v[208:211], v[96:99]
	v_mfma_f32_16x16x32_bf16 v[84:87], v[148:151], v[216:219], v[84:87]
	v_mfma_f32_16x16x32_bf16 v[80:83], v[156:159], v[216:219], v[80:83]
	v_mfma_f32_16x16x32_bf16 v[68:71], v[148:151], v[224:227], v[68:71]
	v_mfma_f32_16x16x32_bf16 v[64:67], v[156:159], v[224:227], v[64:67]
	s_setprio 0
	s_barrier
	s_add_i32 s22, s66, s30
	v_lshl_add_u64 v[182:183], v[182:183], 0, s[14:15]
	s_mov_b32 m0, s22
	ds_read_b128 v[178:181], v191 offset:49152
	ds_read_b128 v[196:199], v191 offset:50176
	ds_read_b128 v[204:207], v191 offset:51200
	ds_read_b128 v[208:211], v191 offset:52224
	ds_read_b128 v[212:215], v191 offset:53248
	ds_read_b128 v[216:219], v191 offset:54272
	ds_read_b128 v[220:223], v191 offset:55296
	ds_read_b128 v[224:227], v191 offset:56320
	global_load_lds_dwordx4 v[182:183], off
	s_add_i32 m0, s22, 0x2000
	s_add_u32 s22, s26, 0xb0080
	v_lshl_add_u64 v[182:183], v[200:201], 0, s[14:15]
	s_addc_u32 s23, s27, 0
	s_add_i32 s26, s67, s30
	global_load_lds_dwordx4 v[182:183], off
	v_lshl_add_u64 v[182:183], s[22:23], 0, v[162:163]
	s_mov_b32 m0, s26
	s_nop 0
	global_load_lds_dwordx4 v[182:183], off
	v_lshl_add_u64 v[182:183], s[22:23], 0, v[166:167]
	s_add_i32 m0, s26, 0x2000
	s_nop 0
	global_load_lds_dwordx4 v[182:183], off
	s_waitcnt vmcnt(4)
	s_waitcnt lgkmcnt(0)
	s_barrier
	s_setprio 1
	s_waitcnt lgkmcnt(0)
	v_mfma_f32_16x16x32_bf16 v[60:63], v[128:131], v[178:181], v[60:63]
	v_mfma_f32_16x16x32_bf16 v[56:59], v[136:139], v[178:181], v[56:59]
	v_mfma_f32_16x16x32_bf16 v[44:47], v[128:131], v[204:207], v[44:47]
	v_mfma_f32_16x16x32_bf16 v[40:43], v[136:139], v[204:207], v[40:43]
	v_mfma_f32_16x16x32_bf16 v[28:31], v[128:131], v[212:215], v[28:31]
	v_mfma_f32_16x16x32_bf16 v[24:27], v[136:139], v[212:215], v[24:27]
	v_mfma_f32_16x16x32_bf16 v[12:15], v[128:131], v[220:223], v[12:15]
	v_mfma_f32_16x16x32_bf16 v[8:11], v[136:139], v[220:223], v[8:11]
	v_mfma_f32_16x16x32_bf16 v[60:63], v[132:135], v[196:199], v[60:63]
	v_mfma_f32_16x16x32_bf16 v[56:59], v[140:143], v[196:199], v[56:59]
	v_mfma_f32_16x16x32_bf16 v[44:47], v[132:135], v[208:211], v[44:47]
	v_mfma_f32_16x16x32_bf16 v[40:43], v[140:143], v[208:211], v[40:43]
	v_mfma_f32_16x16x32_bf16 v[28:31], v[132:135], v[216:219], v[28:31]
	v_mfma_f32_16x16x32_bf16 v[24:27], v[140:143], v[216:219], v[24:27]
	v_mfma_f32_16x16x32_bf16 v[12:15], v[132:135], v[224:227], v[12:15]
	v_mfma_f32_16x16x32_bf16 v[8:11], v[140:143], v[224:227], v[8:11]
	s_setprio 0
	s_setprio 1
	v_mfma_f32_16x16x32_bf16 v[52:55], v[144:147], v[178:181], v[52:55]
	v_mfma_f32_16x16x32_bf16 v[48:51], v[152:155], v[178:181], v[48:51]
	v_mfma_f32_16x16x32_bf16 v[36:39], v[144:147], v[204:207], v[36:39]
	v_mfma_f32_16x16x32_bf16 v[32:35], v[152:155], v[204:207], v[32:35]
	v_mfma_f32_16x16x32_bf16 v[20:23], v[144:147], v[212:215], v[20:23]
	v_mfma_f32_16x16x32_bf16 v[16:19], v[152:155], v[212:215], v[16:19]
	v_mfma_f32_16x16x32_bf16 v[4:7], v[144:147], v[220:223], v[4:7]
	v_mfma_f32_16x16x32_bf16 v[0:3], v[152:155], v[220:223], v[0:3]
	v_mfma_f32_16x16x32_bf16 v[52:55], v[148:151], v[196:199], v[52:55]
	v_mfma_f32_16x16x32_bf16 v[48:51], v[156:159], v[196:199], v[48:51]
	v_mfma_f32_16x16x32_bf16 v[36:39], v[148:151], v[208:211], v[36:39]
	v_mfma_f32_16x16x32_bf16 v[32:35], v[156:159], v[208:211], v[32:35]
	v_mfma_f32_16x16x32_bf16 v[20:23], v[148:151], v[216:219], v[20:23]
	v_mfma_f32_16x16x32_bf16 v[16:19], v[156:159], v[216:219], v[16:19]
	v_mfma_f32_16x16x32_bf16 v[4:7], v[148:151], v[224:227], v[4:7]
	v_mfma_f32_16x16x32_bf16 v[0:3], v[156:159], v[224:227], v[0:3]
	s_setprio 0
	s_barrier
	s_add_i32 s65, s65, 2
	s_add_u32 s62, s62, 0x100
	s_addc_u32 s63, s63, 0
	s_cmp_gt_u32 s65, 41
	s_mov_b64 s[22:23], s[24:25]
	s_cbranch_scc0 .LBB0_908
	s_and_b64 vcc, exec, s[16:17]
	s_cbranch_vccz .LBB0_911
	s_barrier
